# GEMM main loops: LDS-DMA address via SALU saddr form instead of 2x v_lshl_add_u64 per DMA (84 sites)
# baseline (speedup 1.0000x reference)
.LBB0_210:
	s_waitcnt vmcnt(6) lgkmcnt(0)
	s_barrier
	s_waitcnt lgkmcnt(0)
	v_mfma_f32_16x16x32_bf16 v[124:127], v[52:55], v[64:67], v[124:127]
	s_mul_i32 s23, s26, 0xc000
	s_add_i32 s27, s23, 0xffff4000
	v_mfma_f32_16x16x32_bf16 v[120:123], v[48:51], v[64:67], v[120:123]
	s_cmp_lg_u32 s26, 0
	s_cselect_b32 s27, s27, 0x18000
	s_add_i32 s33, s16, s27
	v_mfma_f32_16x16x32_bf16 v[116:119], v[44:47], v[64:67], v[116:119]
	v_mfma_f32_16x16x32_bf16 v[64:67], v[40:43], v[64:67], v[112:115]
	v_mfma_f32_16x16x32_bf16 v[108:111], v[52:55], v[56:59], v[108:111]
	v_mfma_f32_16x16x32_bf16 v[104:107], v[48:51], v[56:59], v[104:107]
	v_mfma_f32_16x16x32_bf16 v[100:103], v[44:47], v[56:59], v[100:103]
	v_mfma_f32_16x16x32_bf16 v[56:59], v[40:43], v[56:59], v[96:99]
	s_add_u32 s60, s10, s6
	v_mov_b32_e32 v150, v178
	s_addc_u32 s61, s11, s7
	s_mov_b32 m0, s33
	s_add_u32 s98, s60, s72
	s_addc_u32 s99, s61, s73
	global_load_lds_dwordx4 v178, s[98:99]
	v_mfma_f32_16x16x32_bf16 v[92:95], v[52:55], v[36:39], v[92:95]
	v_mfma_f32_16x16x32_bf16 v[88:91], v[48:51], v[36:39], v[88:91]
	v_mfma_f32_16x16x32_bf16 v[84:87], v[44:47], v[36:39], v[84:87]
	v_mfma_f32_16x16x32_bf16 v[36:39], v[40:43], v[36:39], v[80:83]
	v_mfma_f32_16x16x32_bf16 v[52:55], v[52:55], v[32:35], v[76:79]
	v_mfma_f32_16x16x32_bf16 v[48:51], v[48:51], v[32:35], v[72:75]
	v_mfma_f32_16x16x32_bf16 v[44:47], v[44:47], v[32:35], v[68:71]
	v_mfma_f32_16x16x32_bf16 v[32:35], v[40:43], v[32:35], v[60:63]
	v_mov_b32_e32 v150, v179
	s_add_i32 m0, s33, 0x400
	s_add_u32 s100, s60, s74
	s_addc_u32 s101, s61, s75
	global_load_lds_dwordx4 v179, s[100:101]
	v_mfma_f32_16x16x32_bf16 v[124:127], v[20:23], v[28:31], v[124:127]
	v_mfma_f32_16x16x32_bf16 v[120:123], v[16:19], v[28:31], v[120:123]
	v_mfma_f32_16x16x32_bf16 v[116:119], v[12:15], v[28:31], v[116:119]
	v_mfma_f32_16x16x32_bf16 v[112:115], v[8:11], v[28:31], v[64:67]
	v_mfma_f32_16x16x32_bf16 v[108:111], v[20:23], v[24:27], v[108:111]
	v_mfma_f32_16x16x32_bf16 v[104:107], v[16:19], v[24:27], v[104:107]
	v_mfma_f32_16x16x32_bf16 v[100:103], v[12:15], v[24:27], v[100:103]
	v_mfma_f32_16x16x32_bf16 v[96:99], v[8:11], v[24:27], v[56:59]
	v_mov_b32_e32 v150, v178
	s_add_i32 m0, s33, 0x800
	s_add_u32 s98, s60, s76
	s_addc_u32 s99, s61, s77
	global_load_lds_dwordx4 v178, s[98:99]
	v_mfma_f32_16x16x32_bf16 v[92:95], v[20:23], v[4:7], v[92:95]
	s_waitcnt lgkmcnt(0)
	v_mfma_f32_16x16x32_bf16 v[88:91], v[16:19], v[4:7], v[88:91]
	v_mfma_f32_16x16x32_bf16 v[84:87], v[12:15], v[4:7], v[84:87]
	v_mfma_f32_16x16x32_bf16 v[80:83], v[8:11], v[4:7], v[36:39]
	v_mfma_f32_16x16x32_bf16 v[76:79], v[20:23], v[0:3], v[52:55]
	v_mfma_f32_16x16x32_bf16 v[72:75], v[16:19], v[0:3], v[48:51]
	v_mfma_f32_16x16x32_bf16 v[68:71], v[12:15], v[0:3], v[44:47]
	v_mfma_f32_16x16x32_bf16 v[60:63], v[8:11], v[0:3], v[32:35]
	s_barrier
	s_add_i32 s23, s23, 0
	v_add_u32_e32 v0, s23, v164
	v_add3_u32 v1, v0, s21, v169
	v_add3_u32 v0, v0, s20, v169
	v_add_u32_e32 v8, s23, v165
	ds_read_b128 v[64:67], v1
	ds_read_b128 v[56:59], v1 offset:2048
	ds_read_b128 v[36:39], v1 offset:4096
	ds_read_b128 v[32:35], v1 offset:6144
	ds_read_b128 v[52:55], v0 offset:32768
	ds_read_b128 v[48:51], v0 offset:34816
	ds_read_b128 v[44:47], v0 offset:36864
	ds_read_b128 v[40:43], v0 offset:38912
	v_add3_u32 v0, v8, s21, v169
	v_add3_u32 v8, v8, s20, v169
	ds_read_b128 v[28:31], v0
	ds_read_b128 v[24:27], v0 offset:2048
	ds_read_b128 v[4:7], v0 offset:4096
	ds_read_b128 v[0:3], v0 offset:6144
	ds_read_b128 v[20:23], v8 offset:32768
	ds_read_b128 v[16:19], v8 offset:34816
	ds_read_b128 v[12:15], v8 offset:36864
	ds_read_b128 v[8:11], v8 offset:38912
	s_waitcnt lgkmcnt(0)
	s_add_i32 s23, s27, 0
	s_add_i32 s27, s23, s3
	v_mov_b32_e32 v150, v179
	s_add_i32 m0, s27, 0xc00
	s_nop 0
	s_add_u32 s100, s60, s78
	s_addc_u32 s101, s61, s79
	s_add_u32 s60, vcc_lo, s6
	v_mov_b32_e32 v150, v178
	s_addc_u32 s61, vcc_hi, s7
	global_load_lds_dwordx4 v179, s[100:101]
	s_add_i32 s23, s23, s17
	s_add_i32 m0, s23, 0x8000
	v_mov_b32_e32 v150, v179
	s_add_u32 s98, s60, s80
	s_addc_u32 s99, s61, s81
	global_load_lds_dwordx4 v178, s[98:99]
	s_add_i32 m0, s23, 0x8400
	s_add_u32 s100, s60, s82
	s_addc_u32 s101, s61, s83
	global_load_lds_dwordx4 v179, s[100:101]
	s_add_i32 s23, s26, 1
	s_cmp_lg_u32 s26, 2
	s_cselect_b32 s26, s23, 0
	s_add_u32 s6, s6, 0x80
	s_addc_u32 s7, s7, 0
	s_cmpk_eq_i32 s6, 0x680
	s_cbranch_scc0 .LBB0_210
	s_waitcnt vmcnt(6) lgkmcnt(0)
	s_barrier
	s_waitcnt lgkmcnt(0)
	v_mfma_f32_16x16x32_bf16 v[124:127], v[52:55], v[64:67], v[124:127]
	s_mul_i32 s11, s26, 0xc000
	s_add_i32 s6, s11, 0xffff4000
	v_mfma_f32_16x16x32_bf16 v[120:123], v[48:51], v[64:67], v[120:123]
	s_cmp_lg_u32 s26, 0
	s_cselect_b32 s10, s6, 0x18000
	s_andn2_b64 vcc, exec, s[94:95]
	v_mfma_f32_16x16x32_bf16 v[116:119], v[44:47], v[64:67], v[116:119]
	v_mfma_f32_16x16x32_bf16 v[64:67], v[40:43], v[64:67], v[112:115]
	v_mfma_f32_16x16x32_bf16 v[108:111], v[52:55], v[56:59], v[108:111]
	s_nop 1
	v_cndmask_b32_e64 v112, 0, 1, s[94:95]
	v_cmp_ne_u32_e64 s[6:7], 1, v112
	v_mfma_f32_16x16x32_bf16 v[104:107], v[48:51], v[56:59], v[104:107]
	v_mfma_f32_16x16x32_bf16 v[100:103], v[44:47], v[56:59], v[100:103]
	v_mfma_f32_16x16x32_bf16 v[140:143], v[40:43], v[56:59], v[96:99]
	s_cbranch_vccnz .LBB0_213
	s_add_u32 s60, s66, s8
	v_mov_b32_e32 v56, v178
	s_addc_u32 s61, s67, s9
	s_add_i32 m0, s16, s10
	s_nop 0
	global_load_lds_dwordx4 v56, s[60:61]

.LBB0_237:
	s_waitcnt vmcnt(6) lgkmcnt(0)
	s_barrier
	s_mul_i32 s23, s10, 0xc000
	s_add_i32 s26, s23, 0
	v_add_u32_e32 v80, s26, v164
	v_add_u32_e32 v112, s26, v165
	v_add3_u32 v76, v80, s21, v169
	v_add3_u32 v92, v80, s20, v169
	v_add3_u32 v108, v112, s21, v169
	v_add3_u32 v124, v112, s20, v169
	ds_read_b128 v[64:67], v76
	ds_read_b128 v[68:71], v76 offset:2048
	ds_read_b128 v[72:75], v76 offset:4096
	ds_read_b128 v[76:79], v76 offset:6144
	ds_read_b128 v[80:83], v92 offset:32768
	ds_read_b128 v[84:87], v92 offset:34816
	ds_read_b128 v[88:91], v92 offset:36864
	ds_read_b128 v[92:95], v92 offset:38912
	ds_read_b128 v[96:99], v108
	ds_read_b128 v[100:103], v108 offset:2048
	ds_read_b128 v[104:107], v108 offset:4096
	ds_read_b128 v[108:111], v108 offset:6144
	ds_read_b128 v[112:115], v124 offset:32768
	ds_read_b128 v[116:119], v124 offset:34816
	ds_read_b128 v[120:123], v124 offset:36864
	ds_read_b128 v[124:127], v124 offset:38912
	s_waitcnt lgkmcnt(0)
	s_add_i32 s23, s23, 0xffff4000
	s_cmp_lg_u32 s10, 0
	s_cselect_b32 s23, s23, 0x18000
	s_add_i32 s29, s23, 0
	s_add_u32 s26, s6, s4
	s_addc_u32 s27, s7, s5
	s_add_i32 s60, s29, s3
	v_mov_b32_e32 v150, v179
	s_add_i32 m0, s60, 0xc00
	s_add_u32 s60, s11, s4
	v_mov_b32_e32 v150, v178
	s_addc_u32 s61, s22, s5
	s_add_u32 s98, s26, s78
	s_addc_u32 s99, s27, s79
	global_load_lds_dwordx4 v179, s[98:99]
	s_add_i32 s29, s29, s17
	s_add_i32 m0, s29, 0x8000
	v_mov_b32_e32 v150, v179
	s_add_u32 s100, s60, s80
	s_addc_u32 s101, s61, s81
	global_load_lds_dwordx4 v178, s[100:101]
	s_add_i32 m0, s29, 0x8400
	s_add_u32 s98, s60, s82
	s_addc_u32 s99, s61, s83
	global_load_lds_dwordx4 v179, s[98:99]
	s_waitcnt lgkmcnt(0)
	s_barrier
	s_waitcnt lgkmcnt(0)
	v_mfma_f32_16x16x32_bf16 v[60:63], v[80:83], v[64:67], v[60:63]
	s_add_i32 s23, s16, s23
	v_mfma_f32_16x16x32_bf16 v[56:59], v[84:87], v[64:67], v[56:59]
	v_mfma_f32_16x16x32_bf16 v[52:55], v[88:91], v[64:67], v[52:55]
	v_mfma_f32_16x16x32_bf16 v[48:51], v[92:95], v[64:67], v[48:51]
	v_mfma_f32_16x16x32_bf16 v[44:47], v[80:83], v[68:71], v[44:47]
	v_mfma_f32_16x16x32_bf16 v[40:43], v[84:87], v[68:71], v[40:43]
	v_mfma_f32_16x16x32_bf16 v[36:39], v[88:91], v[68:71], v[36:39]
	v_mfma_f32_16x16x32_bf16 v[28:31], v[92:95], v[68:71], v[28:31]
	v_mov_b32_e32 v150, v178
	s_mov_b32 m0, s23
	s_add_u32 s100, s26, s72
	s_addc_u32 s101, s27, s73
	global_load_lds_dwordx4 v178, s[100:101]
	v_mfma_f32_16x16x32_bf16 v[24:27], v[80:83], v[72:75], v[24:27]
	v_mfma_f32_16x16x32_bf16 v[20:23], v[84:87], v[72:75], v[20:23]
	v_mfma_f32_16x16x32_bf16 v[16:19], v[88:91], v[72:75], v[16:19]
	v_mfma_f32_16x16x32_bf16 v[12:15], v[92:95], v[72:75], v[12:15]
	v_mfma_f32_16x16x32_bf16 v[8:11], v[80:83], v[76:79], v[8:11]
	v_mfma_f32_16x16x32_bf16 v[4:7], v[84:87], v[76:79], v[4:7]
	v_mfma_f32_16x16x32_bf16 v[0:3], v[88:91], v[76:79], v[0:3]
	v_mfma_f32_16x16x32_bf16 v[32:35], v[92:95], v[76:79], v[32:35]
	v_mov_b32_e32 v150, v179
	s_add_i32 m0, s23, 0x400
	s_add_u32 s98, s26, s74
	s_addc_u32 s99, s27, s75
	global_load_lds_dwordx4 v179, s[98:99]
	v_mfma_f32_16x16x32_bf16 v[60:63], v[112:115], v[96:99], v[60:63]
	v_mfma_f32_16x16x32_bf16 v[56:59], v[116:119], v[96:99], v[56:59]
	v_mfma_f32_16x16x32_bf16 v[52:55], v[120:123], v[96:99], v[52:55]
	v_mfma_f32_16x16x32_bf16 v[48:51], v[124:127], v[96:99], v[48:51]
	v_mfma_f32_16x16x32_bf16 v[44:47], v[112:115], v[100:103], v[44:47]
	v_mfma_f32_16x16x32_bf16 v[40:43], v[116:119], v[100:103], v[40:43]
	v_mfma_f32_16x16x32_bf16 v[36:39], v[120:123], v[100:103], v[36:39]
	v_mfma_f32_16x16x32_bf16 v[28:31], v[124:127], v[100:103], v[28:31]
	v_mov_b32_e32 v150, v178
	s_add_i32 m0, s23, 0x800
	s_add_u32 s100, s26, s76
	s_addc_u32 s101, s27, s77
	global_load_lds_dwordx4 v178, s[100:101]
	s_add_i32 s23, s10, 1
	v_mfma_f32_16x16x32_bf16 v[24:27], v[112:115], v[104:107], v[24:27]
	s_cmp_lg_u32 s10, 2
	s_cselect_b32 s10, s23, 0
	s_add_u32 s4, s4, 0x80
	v_mfma_f32_16x16x32_bf16 v[20:23], v[116:119], v[104:107], v[20:23]
	s_addc_u32 s5, s5, 0
	s_cmpk_eq_i32 s4, 0x680
	v_mfma_f32_16x16x32_bf16 v[16:19], v[120:123], v[104:107], v[16:19]
	v_mfma_f32_16x16x32_bf16 v[12:15], v[124:127], v[104:107], v[12:15]
	v_mfma_f32_16x16x32_bf16 v[8:11], v[112:115], v[108:111], v[8:11]
	v_mfma_f32_16x16x32_bf16 v[4:7], v[116:119], v[108:111], v[4:7]
	v_mfma_f32_16x16x32_bf16 v[0:3], v[120:123], v[108:111], v[0:3]
	v_mfma_f32_16x16x32_bf16 v[32:35], v[124:127], v[108:111], v[32:35]
	s_cbranch_scc0 .LBB0_237
	s_waitcnt vmcnt(6) lgkmcnt(0)
	s_barrier
	s_mul_i32 s4, s10, 0xc000
	s_add_i32 s4, s4, 0
	v_add_u32_e32 v64, s4, v164
	v_add3_u32 v65, v64, s21, v169
	v_add3_u32 v64, v64, s20, v169
	v_add_u32_e32 v68, s4, v165
	ds_read_b128 v[124:127], v65
	ds_read_b128 v[120:123], v65 offset:2048
	ds_read_b128 v[100:103], v65 offset:4096
	ds_read_b128 v[96:99], v65 offset:6144
	ds_read_b128 v[108:111], v64 offset:32768
	ds_read_b128 v[112:115], v64 offset:34816
	ds_read_b128 v[116:119], v64 offset:36864
	ds_read_b128 v[104:107], v64 offset:38912
	v_add3_u32 v64, v68, s21, v169
	v_add3_u32 v68, v68, s20, v169
	ds_read_b128 v[92:95], v64
	ds_read_b128 v[88:91], v64 offset:2048
	ds_read_b128 v[72:75], v64 offset:4096
	ds_read_b128 v[64:67], v64 offset:6144
	ds_read_b128 v[76:79], v68 offset:32768
	ds_read_b128 v[80:83], v68 offset:34816
	ds_read_b128 v[84:87], v68 offset:36864
	ds_read_b128 v[68:71], v68 offset:38912
	s_waitcnt lgkmcnt(0)
	v_sub_co_u32_e64 v128, s[4:5], s10, 1
	s_and_b64 s[4:5], s[4:5], exec
	v_readfirstlane_b32 s4, v128
	s_cselect_b32 s23, 2, s4
	v_cndmask_b32_e64 v128, 0, 1, s[92:93]
	s_mov_b64 s[4:5], -1
	v_cmp_ne_u32_e64 s[6:7], 1, v128
	s_andn2_b64 vcc, exec, s[92:93]
	s_mul_i32 s22, s23, 0xc000
	s_cbranch_vccnz .LBB0_240
	s_mul_i32 s11, s23, 0xc000
	s_mov_b64 s[4:5], 0

.LBB0_459:
	s_waitcnt vmcnt(6) lgkmcnt(0)
	s_barrier
	s_waitcnt lgkmcnt(0)
	v_mfma_f32_16x16x32_bf16 v[124:127], v[52:55], v[64:67], v[124:127]
	s_mul_i32 s66, s29, 0xc000
	s_add_i32 s64, s66, 0xffff4000
	v_mfma_f32_16x16x32_bf16 v[120:123], v[48:51], v[64:67], v[120:123]
	s_cmp_lg_u32 s29, 0
	s_cselect_b32 s67, s64, 0x18000
	s_add_i32 s61, s16, s67
	v_mfma_f32_16x16x32_bf16 v[116:119], v[44:47], v[64:67], v[116:119]
	v_mfma_f32_16x16x32_bf16 v[64:67], v[40:43], v[64:67], v[112:115]
	v_mfma_f32_16x16x32_bf16 v[108:111], v[52:55], v[56:59], v[108:111]
	v_mfma_f32_16x16x32_bf16 v[104:107], v[48:51], v[56:59], v[104:107]
	v_mfma_f32_16x16x32_bf16 v[100:103], v[44:47], v[56:59], v[100:103]
	v_mfma_f32_16x16x32_bf16 v[56:59], v[40:43], v[56:59], v[96:99]
	s_add_u32 s64, s10, s6
	v_mov_b32_e32 v150, v162
	s_addc_u32 s65, s11, s7
	s_mov_b32 m0, s61
	s_add_u32 s98, s64, s48
	s_addc_u32 s99, s65, s49
	global_load_lds_dwordx4 v162, s[98:99]
	v_mfma_f32_16x16x32_bf16 v[92:95], v[52:55], v[36:39], v[92:95]
	v_mfma_f32_16x16x32_bf16 v[88:91], v[48:51], v[36:39], v[88:91]
	v_mfma_f32_16x16x32_bf16 v[84:87], v[44:47], v[36:39], v[84:87]
	v_mfma_f32_16x16x32_bf16 v[36:39], v[40:43], v[36:39], v[80:83]
	v_mfma_f32_16x16x32_bf16 v[52:55], v[52:55], v[32:35], v[76:79]
	v_mfma_f32_16x16x32_bf16 v[48:51], v[48:51], v[32:35], v[72:75]
	v_mfma_f32_16x16x32_bf16 v[44:47], v[44:47], v[32:35], v[68:71]
	v_mfma_f32_16x16x32_bf16 v[32:35], v[40:43], v[32:35], v[60:63]
	v_mov_b32_e32 v150, v163
	s_add_i32 m0, s61, 0x400
	s_add_u32 s100, s64, s50
	s_addc_u32 s101, s65, s51
	global_load_lds_dwordx4 v163, s[100:101]
	v_mfma_f32_16x16x32_bf16 v[124:127], v[20:23], v[28:31], v[124:127]
	v_mfma_f32_16x16x32_bf16 v[120:123], v[16:19], v[28:31], v[120:123]
	v_mfma_f32_16x16x32_bf16 v[116:119], v[12:15], v[28:31], v[116:119]
	v_mfma_f32_16x16x32_bf16 v[112:115], v[8:11], v[28:31], v[64:67]
	v_mfma_f32_16x16x32_bf16 v[108:111], v[20:23], v[24:27], v[108:111]
	v_mfma_f32_16x16x32_bf16 v[104:107], v[16:19], v[24:27], v[104:107]
	v_mfma_f32_16x16x32_bf16 v[100:103], v[12:15], v[24:27], v[100:103]
	v_mfma_f32_16x16x32_bf16 v[96:99], v[8:11], v[24:27], v[56:59]
	v_mov_b32_e32 v150, v162
	s_add_i32 m0, s61, 0x800
	s_add_u32 s98, s64, s68
	s_addc_u32 s99, s65, s69
	global_load_lds_dwordx4 v162, s[98:99]
	v_mfma_f32_16x16x32_bf16 v[92:95], v[20:23], v[4:7], v[92:95]
	s_waitcnt lgkmcnt(0)
	v_mfma_f32_16x16x32_bf16 v[88:91], v[16:19], v[4:7], v[88:91]
	v_mfma_f32_16x16x32_bf16 v[84:87], v[12:15], v[4:7], v[84:87]
	v_mfma_f32_16x16x32_bf16 v[80:83], v[8:11], v[4:7], v[36:39]
	v_mfma_f32_16x16x32_bf16 v[76:79], v[20:23], v[0:3], v[52:55]
	v_mfma_f32_16x16x32_bf16 v[72:75], v[16:19], v[0:3], v[48:51]
	v_mfma_f32_16x16x32_bf16 v[68:71], v[12:15], v[0:3], v[44:47]
	v_mfma_f32_16x16x32_bf16 v[60:63], v[8:11], v[0:3], v[32:35]
	s_barrier
	s_add_i32 s61, s66, 0
	v_add_u32_e32 v0, s61, v157
	v_add3_u32 v1, v0, s25, v169
	v_add3_u32 v0, v0, s24, v169
	v_add_u32_e32 v8, s61, v158
	ds_read_b128 v[64:67], v1
	ds_read_b128 v[56:59], v1 offset:2048
	ds_read_b128 v[36:39], v1 offset:4096
	ds_read_b128 v[32:35], v1 offset:6144
	ds_read_b128 v[52:55], v0 offset:32768
	ds_read_b128 v[48:51], v0 offset:34816
	ds_read_b128 v[44:47], v0 offset:36864
	ds_read_b128 v[40:43], v0 offset:38912
	v_add3_u32 v0, v8, s25, v169
	v_add3_u32 v8, v8, s24, v169
	ds_read_b128 v[28:31], v0
	ds_read_b128 v[24:27], v0 offset:2048
	ds_read_b128 v[4:7], v0 offset:4096
	ds_read_b128 v[0:3], v0 offset:6144
	ds_read_b128 v[20:23], v8 offset:32768
	ds_read_b128 v[16:19], v8 offset:34816
	ds_read_b128 v[12:15], v8 offset:36864
	ds_read_b128 v[8:11], v8 offset:38912
	s_waitcnt lgkmcnt(0)
	s_add_i32 s61, s67, 0
	v_mov_b32_e32 v150, v163
	s_nop 0
	s_add_u32 s100, s64, s70
	s_addc_u32 s101, s65, s71
	s_add_i32 s64, s61, s3
	s_add_i32 m0, s64, 0xc00
	s_add_u32 s64, vcc_lo, s6
	v_mov_b32_e32 v150, v162
	s_addc_u32 s65, vcc_hi, s7
	global_load_lds_dwordx4 v163, s[100:101]
	s_add_i32 s61, s61, s17
	s_add_i32 m0, s61, 0x8000
	v_mov_b32_e32 v150, v163
	s_add_u32 s98, s64, s72
	s_addc_u32 s99, s65, s73
	global_load_lds_dwordx4 v162, s[98:99]
	s_add_i32 m0, s61, 0x8400
	s_add_u32 s100, s64, s74
	s_addc_u32 s101, s65, s75
	global_load_lds_dwordx4 v163, s[100:101]
	s_add_i32 s61, s29, 1
	s_cmp_lg_u32 s29, 2
	s_cselect_b32 s29, s61, 0
	s_add_u32 s6, s6, 0x80
	s_addc_u32 s7, s7, 0
	s_cmpk_eq_i32 s6, 0x680
	s_cbranch_scc0 .LBB0_459
	s_waitcnt vmcnt(6) lgkmcnt(0)
	s_barrier
	s_waitcnt lgkmcnt(0)
	v_mfma_f32_16x16x32_bf16 v[124:127], v[52:55], v[64:67], v[124:127]
	s_mul_i32 s11, s29, 0xc000
	s_add_i32 s6, s11, 0xffff4000
	v_mfma_f32_16x16x32_bf16 v[120:123], v[48:51], v[64:67], v[120:123]
	s_cmp_lg_u32 s29, 0
	s_cselect_b32 s10, s6, 0x18000
	s_andn2_b64 vcc, exec, s[12:13]
	v_mfma_f32_16x16x32_bf16 v[116:119], v[44:47], v[64:67], v[116:119]
	v_mfma_f32_16x16x32_bf16 v[64:67], v[40:43], v[64:67], v[112:115]
	v_mfma_f32_16x16x32_bf16 v[108:111], v[52:55], v[56:59], v[108:111]
	s_nop 1
	v_cndmask_b32_e64 v112, 0, 1, s[12:13]
	v_cmp_ne_u32_e64 s[6:7], 1, v112
	v_mfma_f32_16x16x32_bf16 v[104:107], v[48:51], v[56:59], v[104:107]
	v_mfma_f32_16x16x32_bf16 v[100:103], v[44:47], v[56:59], v[100:103]
	v_mfma_f32_16x16x32_bf16 v[140:143], v[40:43], v[56:59], v[96:99]
	s_cbranch_vccnz .LBB0_462
	s_add_u32 s64, s8, s94
	v_mov_b32_e32 v56, v162
	s_addc_u32 s65, s9, s95
	s_add_i32 m0, s16, s10
	s_nop 0
	global_load_lds_dwordx4 v56, s[64:65]

.LBB0_486:
	s_waitcnt vmcnt(6) lgkmcnt(0)
	s_barrier
	s_mul_i32 s19, s18, 0xc000
	s_add_i32 s26, s19, 0
	v_add_u32_e32 v80, s26, v157
	v_add_u32_e32 v112, s26, v158
	v_add3_u32 v76, v80, s25, v169
	v_add3_u32 v92, v80, s24, v169
	v_add3_u32 v108, v112, s25, v169
	v_add3_u32 v124, v112, s24, v169
	ds_read_b128 v[64:67], v76
	ds_read_b128 v[68:71], v76 offset:2048
	ds_read_b128 v[72:75], v76 offset:4096
	ds_read_b128 v[76:79], v76 offset:6144
	ds_read_b128 v[80:83], v92 offset:32768
	ds_read_b128 v[84:87], v92 offset:34816
	ds_read_b128 v[88:91], v92 offset:36864
	ds_read_b128 v[92:95], v92 offset:38912
	ds_read_b128 v[96:99], v108
	ds_read_b128 v[100:103], v108 offset:2048
	ds_read_b128 v[104:107], v108 offset:4096
	ds_read_b128 v[108:111], v108 offset:6144
	ds_read_b128 v[112:115], v124 offset:32768
	ds_read_b128 v[116:119], v124 offset:34816
	ds_read_b128 v[120:123], v124 offset:36864
	ds_read_b128 v[124:127], v124 offset:38912
	s_waitcnt lgkmcnt(0)
	s_add_i32 s19, s19, 0xffff4000
	s_cmp_lg_u32 s18, 0
	s_cselect_b32 s19, s19, 0x18000
	s_add_i32 s26, s19, 0
	s_add_u32 s64, s6, s4
	s_addc_u32 s65, s7, s5
	s_add_i32 s66, s26, s3
	v_mov_b32_e32 v150, v163
	s_add_i32 m0, s66, 0xc00
	s_add_u32 s66, s29, s4
	v_mov_b32_e32 v150, v162
	s_addc_u32 s67, s92, s5
	s_add_u32 s98, s64, s70
	s_addc_u32 s99, s65, s71
	global_load_lds_dwordx4 v163, s[98:99]
	s_add_i32 s26, s26, s17
	s_add_i32 m0, s26, 0x8000
	v_mov_b32_e32 v150, v163
	s_add_u32 s100, s66, s72
	s_addc_u32 s101, s67, s73
	global_load_lds_dwordx4 v162, s[100:101]
	s_add_i32 m0, s26, 0x8400
	s_add_u32 s98, s66, s74
	s_addc_u32 s99, s67, s75
	global_load_lds_dwordx4 v163, s[98:99]
	s_waitcnt lgkmcnt(0)
	s_barrier
	s_waitcnt lgkmcnt(0)
	v_mfma_f32_16x16x32_bf16 v[56:59], v[80:83], v[64:67], v[56:59]
	s_add_i32 s19, s16, s19
	v_mfma_f32_16x16x32_bf16 v[52:55], v[84:87], v[64:67], v[52:55]
	v_mfma_f32_16x16x32_bf16 v[48:51], v[88:91], v[64:67], v[48:51]
	v_mfma_f32_16x16x32_bf16 v[44:47], v[92:95], v[64:67], v[44:47]
	v_mfma_f32_16x16x32_bf16 v[40:43], v[80:83], v[68:71], v[40:43]
	v_mfma_f32_16x16x32_bf16 v[36:39], v[84:87], v[68:71], v[36:39]
	v_mfma_f32_16x16x32_bf16 v[32:35], v[88:91], v[68:71], v[32:35]
	v_mfma_f32_16x16x32_bf16 v[0:3], v[92:95], v[68:71], v[0:3]
	v_mov_b32_e32 v150, v162
	s_mov_b32 m0, s19
	s_add_u32 s100, s64, s48
	s_addc_u32 s101, s65, s49
	global_load_lds_dwordx4 v162, s[100:101]
	v_mfma_f32_16x16x32_bf16 v[28:31], v[80:83], v[72:75], v[28:31]
	v_mfma_f32_16x16x32_bf16 v[24:27], v[84:87], v[72:75], v[24:27]
	v_mfma_f32_16x16x32_bf16 v[20:23], v[88:91], v[72:75], v[20:23]
	v_mfma_f32_16x16x32_bf16 v[16:19], v[92:95], v[72:75], v[16:19]
	v_mfma_f32_16x16x32_bf16 v[12:15], v[80:83], v[76:79], v[12:15]
	v_mfma_f32_16x16x32_bf16 v[8:11], v[84:87], v[76:79], v[8:11]
	v_mfma_f32_16x16x32_bf16 v[4:7], v[88:91], v[76:79], v[4:7]
	v_mfma_f32_16x16x32_bf16 v[60:63], v[92:95], v[76:79], v[60:63]
	v_mov_b32_e32 v150, v163
	s_add_i32 m0, s19, 0x400
	s_add_u32 s98, s64, s50
	s_addc_u32 s99, s65, s51
	global_load_lds_dwordx4 v163, s[98:99]
	v_mfma_f32_16x16x32_bf16 v[56:59], v[112:115], v[96:99], v[56:59]
	v_mfma_f32_16x16x32_bf16 v[52:55], v[116:119], v[96:99], v[52:55]
	v_mfma_f32_16x16x32_bf16 v[48:51], v[120:123], v[96:99], v[48:51]
	v_mfma_f32_16x16x32_bf16 v[44:47], v[124:127], v[96:99], v[44:47]
	v_mfma_f32_16x16x32_bf16 v[40:43], v[112:115], v[100:103], v[40:43]
	v_mfma_f32_16x16x32_bf16 v[36:39], v[116:119], v[100:103], v[36:39]
	v_mfma_f32_16x16x32_bf16 v[32:35], v[120:123], v[100:103], v[32:35]
	v_mfma_f32_16x16x32_bf16 v[0:3], v[124:127], v[100:103], v[0:3]
	v_mov_b32_e32 v150, v162
	s_add_i32 m0, s19, 0x800
	s_add_u32 s100, s64, s68
	s_addc_u32 s101, s65, s69
	global_load_lds_dwordx4 v162, s[100:101]
	s_add_i32 s19, s18, 1
	v_mfma_f32_16x16x32_bf16 v[28:31], v[112:115], v[104:107], v[28:31]
	s_cmp_lg_u32 s18, 2
	s_cselect_b32 s18, s19, 0
	s_add_u32 s4, s4, 0x80
	v_mfma_f32_16x16x32_bf16 v[24:27], v[116:119], v[104:107], v[24:27]
	s_addc_u32 s5, s5, 0
	s_cmpk_eq_i32 s4, 0x680
	v_mfma_f32_16x16x32_bf16 v[20:23], v[120:123], v[104:107], v[20:23]
	v_mfma_f32_16x16x32_bf16 v[16:19], v[124:127], v[104:107], v[16:19]
	v_mfma_f32_16x16x32_bf16 v[12:15], v[112:115], v[108:111], v[12:15]
	v_mfma_f32_16x16x32_bf16 v[8:11], v[116:119], v[108:111], v[8:11]
	v_mfma_f32_16x16x32_bf16 v[4:7], v[120:123], v[108:111], v[4:7]
	v_mfma_f32_16x16x32_bf16 v[60:63], v[124:127], v[108:111], v[60:63]
	s_cbranch_scc0 .LBB0_486
	s_waitcnt vmcnt(6) lgkmcnt(0)
	s_barrier
	s_mul_i32 s4, s18, 0xc000
	s_add_i32 s4, s4, 0
	v_add_u32_e32 v64, s4, v157
	v_add3_u32 v65, v64, s25, v169
	v_add3_u32 v64, v64, s24, v169
	v_add_u32_e32 v68, s4, v158
	ds_read_b128 v[124:127], v65
	ds_read_b128 v[120:123], v65 offset:2048
	ds_read_b128 v[96:99], v65 offset:4096
	ds_read_b128 v[92:95], v65 offset:6144
	ds_read_b128 v[108:111], v64 offset:32768
	ds_read_b128 v[112:115], v64 offset:34816
	ds_read_b128 v[116:119], v64 offset:36864
	ds_read_b128 v[100:103], v64 offset:38912
	v_add3_u32 v64, v68, s25, v169
	v_add3_u32 v68, v68, s24, v169
	ds_read_b128 v[88:91], v64
	ds_read_b128 v[104:107], v64 offset:2048
	ds_read_b128 v[72:75], v64 offset:4096
	ds_read_b128 v[64:67], v64 offset:6144
	ds_read_b128 v[76:79], v68 offset:32768
	ds_read_b128 v[80:83], v68 offset:34816
	ds_read_b128 v[84:87], v68 offset:36864
	ds_read_b128 v[68:71], v68 offset:38912
	s_waitcnt lgkmcnt(0)
	v_sub_co_u32_e64 v128, s[4:5], s18, 1
	s_and_b64 s[4:5], s[4:5], exec
	v_readfirstlane_b32 s4, v128
	s_cselect_b32 s29, 2, s4
	v_cndmask_b32_e64 v128, 0, 1, s[86:87]
	s_mov_b64 s[4:5], -1
	v_cmp_ne_u32_e64 s[6:7], 1, v128
	s_andn2_b64 vcc, exec, s[86:87]
	s_mul_i32 s26, s29, 0xc000
	s_cbranch_vccnz .LBB0_489
	s_mul_i32 s19, s29, 0xc000
	s_mov_b64 s[4:5], 0

.LBB0_640:
	s_waitcnt vmcnt(6) lgkmcnt(0)
	s_barrier
	s_waitcnt lgkmcnt(0)
	v_mfma_f32_16x16x32_bf16 v[124:127], v[52:55], v[64:67], v[124:127]
	s_mul_i32 s86, s97, 0xc000
	s_add_i32 s87, s86, 0xffff4000
	v_mfma_f32_16x16x32_bf16 v[120:123], v[48:51], v[64:67], v[120:123]
	s_cmp_lg_u32 s97, 0
	s_cselect_b32 s87, s87, 0x18000
	s_add_i32 s84, s3, s87
	v_mfma_f32_16x16x32_bf16 v[116:119], v[44:47], v[64:67], v[116:119]
	v_mfma_f32_16x16x32_bf16 v[64:67], v[40:43], v[64:67], v[112:115]
	v_mfma_f32_16x16x32_bf16 v[108:111], v[52:55], v[56:59], v[108:111]
	v_mfma_f32_16x16x32_bf16 v[104:107], v[48:51], v[56:59], v[104:107]
	v_mfma_f32_16x16x32_bf16 v[100:103], v[44:47], v[56:59], v[100:103]
	v_mfma_f32_16x16x32_bf16 v[56:59], v[40:43], v[56:59], v[96:99]
	s_add_u32 s88, s10, s6
	v_mov_b32_e32 v150, v178
	s_addc_u32 s89, s11, s7
	s_mov_b32 m0, s84
	s_add_u32 s98, s88, s72
	s_addc_u32 s99, s89, s73
	global_load_lds_dwordx4 v178, s[98:99]
	v_mfma_f32_16x16x32_bf16 v[92:95], v[52:55], v[36:39], v[92:95]
	v_mfma_f32_16x16x32_bf16 v[88:91], v[48:51], v[36:39], v[88:91]
	v_mfma_f32_16x16x32_bf16 v[84:87], v[44:47], v[36:39], v[84:87]
	v_mfma_f32_16x16x32_bf16 v[36:39], v[40:43], v[36:39], v[80:83]
	v_mfma_f32_16x16x32_bf16 v[52:55], v[52:55], v[32:35], v[76:79]
	v_mfma_f32_16x16x32_bf16 v[48:51], v[48:51], v[32:35], v[72:75]
	v_mfma_f32_16x16x32_bf16 v[44:47], v[44:47], v[32:35], v[68:71]
	v_mfma_f32_16x16x32_bf16 v[32:35], v[40:43], v[32:35], v[60:63]
	v_mov_b32_e32 v150, v179
	s_add_i32 m0, s84, 0x400
	s_add_u32 s100, s88, s74
	s_addc_u32 s101, s89, s75
	global_load_lds_dwordx4 v179, s[100:101]
	v_mfma_f32_16x16x32_bf16 v[124:127], v[20:23], v[28:31], v[124:127]
	v_mfma_f32_16x16x32_bf16 v[120:123], v[16:19], v[28:31], v[120:123]
	v_mfma_f32_16x16x32_bf16 v[116:119], v[12:15], v[28:31], v[116:119]
	v_mfma_f32_16x16x32_bf16 v[112:115], v[8:11], v[28:31], v[64:67]
	v_mfma_f32_16x16x32_bf16 v[108:111], v[20:23], v[24:27], v[108:111]
	v_mfma_f32_16x16x32_bf16 v[104:107], v[16:19], v[24:27], v[104:107]
	v_mfma_f32_16x16x32_bf16 v[100:103], v[12:15], v[24:27], v[100:103]
	v_mfma_f32_16x16x32_bf16 v[96:99], v[8:11], v[24:27], v[56:59]
	v_mov_b32_e32 v150, v178
	s_add_i32 m0, s84, 0x800
	s_add_u32 s98, s88, s76
	s_addc_u32 s99, s89, s77
	global_load_lds_dwordx4 v178, s[98:99]
	v_mfma_f32_16x16x32_bf16 v[92:95], v[20:23], v[4:7], v[92:95]
	s_waitcnt lgkmcnt(0)
	v_mfma_f32_16x16x32_bf16 v[88:91], v[16:19], v[4:7], v[88:91]
	v_mfma_f32_16x16x32_bf16 v[84:87], v[12:15], v[4:7], v[84:87]
	v_mfma_f32_16x16x32_bf16 v[80:83], v[8:11], v[4:7], v[36:39]
	v_mfma_f32_16x16x32_bf16 v[76:79], v[20:23], v[0:3], v[52:55]
	v_mfma_f32_16x16x32_bf16 v[72:75], v[16:19], v[0:3], v[48:51]
	v_mfma_f32_16x16x32_bf16 v[68:71], v[12:15], v[0:3], v[44:47]
	v_mfma_f32_16x16x32_bf16 v[60:63], v[8:11], v[0:3], v[32:35]
	s_barrier
	s_add_i32 s84, s86, 0
	v_add_u32_e32 v0, s84, v157
	v_add3_u32 v1, v0, s18, v169
	v_add3_u32 v0, v0, s17, v169
	v_add_u32_e32 v8, s84, v158
	ds_read_b128 v[64:67], v1
	ds_read_b128 v[56:59], v1 offset:2048
	ds_read_b128 v[36:39], v1 offset:4096
	ds_read_b128 v[32:35], v1 offset:6144
	ds_read_b128 v[52:55], v0 offset:32768
	ds_read_b128 v[48:51], v0 offset:34816
	ds_read_b128 v[44:47], v0 offset:36864
	ds_read_b128 v[40:43], v0 offset:38912
	v_add3_u32 v0, v8, s18, v169
	v_add3_u32 v8, v8, s17, v169
	ds_read_b128 v[28:31], v0
	ds_read_b128 v[24:27], v0 offset:2048
	ds_read_b128 v[4:7], v0 offset:4096
	ds_read_b128 v[0:3], v0 offset:6144
	ds_read_b128 v[20:23], v8 offset:32768
	ds_read_b128 v[16:19], v8 offset:34816
	ds_read_b128 v[12:15], v8 offset:36864
	ds_read_b128 v[8:11], v8 offset:38912
	s_waitcnt lgkmcnt(0)
	s_add_i32 s84, s87, 0
	s_add_i32 s85, s84, s2
	v_mov_b32_e32 v150, v179
	s_add_i32 m0, s85, 0xc00
	s_nop 0
	s_add_u32 s100, s88, s78
	s_addc_u32 s101, s89, s79
	s_add_u32 s88, vcc_lo, s6
	v_mov_b32_e32 v150, v178
	s_addc_u32 s89, vcc_hi, s7
	global_load_lds_dwordx4 v179, s[100:101]
	s_add_i32 s84, s84, s16
	s_add_i32 m0, s84, 0x8000
	v_mov_b32_e32 v150, v179
	s_add_u32 s98, s88, s80
	s_addc_u32 s99, s89, s81
	global_load_lds_dwordx4 v178, s[98:99]
	s_add_i32 m0, s84, 0x8400
	s_add_u32 s100, s88, s82
	s_addc_u32 s101, s89, s83
	global_load_lds_dwordx4 v179, s[100:101]
	s_add_i32 s84, s97, 1
	s_cmp_lg_u32 s97, 2
	s_cselect_b32 s97, s84, 0
	s_add_u32 s6, s6, 0x80
	s_addc_u32 s7, s7, 0
	s_cmpk_eq_i32 s6, 0x680
	s_cbranch_scc0 .LBB0_640
	s_waitcnt vmcnt(6) lgkmcnt(0)
	s_barrier
	s_waitcnt lgkmcnt(0)
	v_mfma_f32_16x16x32_bf16 v[124:127], v[52:55], v[64:67], v[124:127]
	s_mul_i32 s11, s97, 0xc000
	s_add_i32 s6, s11, 0xffff4000
	v_mfma_f32_16x16x32_bf16 v[120:123], v[48:51], v[64:67], v[120:123]
	s_cmp_lg_u32 s97, 0
	s_cselect_b32 s10, s6, 0x18000
	s_andn2_b64 vcc, exec, s[94:95]
	v_mfma_f32_16x16x32_bf16 v[116:119], v[44:47], v[64:67], v[116:119]
	v_mfma_f32_16x16x32_bf16 v[64:67], v[40:43], v[64:67], v[112:115]
	v_mfma_f32_16x16x32_bf16 v[108:111], v[52:55], v[56:59], v[108:111]
	s_nop 1
	v_cndmask_b32_e64 v112, 0, 1, s[94:95]
	v_cmp_ne_u32_e64 s[6:7], 1, v112
	v_mfma_f32_16x16x32_bf16 v[104:107], v[48:51], v[56:59], v[104:107]
	v_mfma_f32_16x16x32_bf16 v[100:103], v[44:47], v[56:59], v[100:103]
	v_mfma_f32_16x16x32_bf16 v[140:143], v[40:43], v[56:59], v[96:99]
	s_cbranch_vccnz .LBB0_643
	s_add_u32 s88, s64, s14
	v_mov_b32_e32 v56, v178
	s_addc_u32 s89, s65, s15
	s_add_i32 m0, s3, s10
	s_nop 0
	global_load_lds_dwordx4 v56, s[88:89]

.LBB0_667:
	s_waitcnt vmcnt(6) lgkmcnt(0)
	s_barrier
	s_mul_i32 s13, s10, 0xc000
	s_add_i32 s20, s13, 0
	v_add_u32_e32 v80, s20, v157
	v_add_u32_e32 v112, s20, v158
	v_add3_u32 v76, v80, s18, v169
	v_add3_u32 v92, v80, s17, v169
	v_add3_u32 v108, v112, s18, v169
	v_add3_u32 v124, v112, s17, v169
	ds_read_b128 v[64:67], v76
	ds_read_b128 v[68:71], v76 offset:2048
	ds_read_b128 v[72:75], v76 offset:4096
	ds_read_b128 v[76:79], v76 offset:6144
	ds_read_b128 v[80:83], v92 offset:32768
	ds_read_b128 v[84:87], v92 offset:34816
	ds_read_b128 v[88:91], v92 offset:36864
	ds_read_b128 v[92:95], v92 offset:38912
	ds_read_b128 v[96:99], v108
	ds_read_b128 v[100:103], v108 offset:2048
	ds_read_b128 v[104:107], v108 offset:4096
	ds_read_b128 v[108:111], v108 offset:6144
	ds_read_b128 v[112:115], v124 offset:32768
	ds_read_b128 v[116:119], v124 offset:34816
	ds_read_b128 v[120:123], v124 offset:36864
	ds_read_b128 v[124:127], v124 offset:38912
	s_waitcnt lgkmcnt(0)
	s_add_i32 s13, s13, 0xffff4000
	s_cmp_lg_u32 s10, 0
	s_cselect_b32 s13, s13, 0x18000
	s_add_i32 s88, s13, 0
	s_add_u32 s20, s6, s4
	s_addc_u32 s21, s7, s5
	s_add_i32 s66, s88, s2
	v_mov_b32_e32 v150, v179
	s_add_i32 m0, s66, 0xc00
	s_add_u32 s66, s11, s4
	v_mov_b32_e32 v150, v178
	s_addc_u32 s67, s12, s5
	s_add_u32 s98, s20, s78
	s_addc_u32 s99, s21, s79
	global_load_lds_dwordx4 v179, s[98:99]
	s_add_i32 s88, s88, s16
	s_add_i32 m0, s88, 0x8000
	v_mov_b32_e32 v150, v179
	s_add_u32 s100, s66, s80
	s_addc_u32 s101, s67, s81
	global_load_lds_dwordx4 v178, s[100:101]
	s_add_i32 m0, s88, 0x8400
	s_add_u32 s98, s66, s82
	s_addc_u32 s99, s67, s83
	global_load_lds_dwordx4 v179, s[98:99]
	s_waitcnt lgkmcnt(0)
	s_barrier
	s_waitcnt lgkmcnt(0)
	v_mfma_f32_16x16x32_bf16 v[60:63], v[80:83], v[64:67], v[60:63]
	s_add_i32 s13, s3, s13
	v_mfma_f32_16x16x32_bf16 v[56:59], v[84:87], v[64:67], v[56:59]
	v_mfma_f32_16x16x32_bf16 v[52:55], v[88:91], v[64:67], v[52:55]
	v_mfma_f32_16x16x32_bf16 v[48:51], v[92:95], v[64:67], v[48:51]
	v_mfma_f32_16x16x32_bf16 v[44:47], v[80:83], v[68:71], v[44:47]
	v_mfma_f32_16x16x32_bf16 v[40:43], v[84:87], v[68:71], v[40:43]
	v_mfma_f32_16x16x32_bf16 v[36:39], v[88:91], v[68:71], v[36:39]
	v_mfma_f32_16x16x32_bf16 v[24:27], v[92:95], v[68:71], v[24:27]
	v_mov_b32_e32 v150, v178
	s_mov_b32 m0, s13
	s_add_u32 s100, s20, s72
	s_addc_u32 s101, s21, s73
	global_load_lds_dwordx4 v178, s[100:101]
	v_mfma_f32_16x16x32_bf16 v[20:23], v[80:83], v[72:75], v[20:23]
	v_mfma_f32_16x16x32_bf16 v[16:19], v[84:87], v[72:75], v[16:19]
	v_mfma_f32_16x16x32_bf16 v[12:15], v[88:91], v[72:75], v[12:15]
	v_mfma_f32_16x16x32_bf16 v[8:11], v[92:95], v[72:75], v[8:11]
	v_mfma_f32_16x16x32_bf16 v[4:7], v[80:83], v[76:79], v[4:7]
	v_mfma_f32_16x16x32_bf16 v[0:3], v[84:87], v[76:79], v[0:3]
	v_mfma_f32_16x16x32_bf16 v[28:31], v[88:91], v[76:79], v[28:31]
	v_mfma_f32_16x16x32_bf16 v[32:35], v[92:95], v[76:79], v[32:35]
	v_mov_b32_e32 v150, v179
	s_add_i32 m0, s13, 0x400
	s_add_u32 s98, s20, s74
	s_addc_u32 s99, s21, s75
	global_load_lds_dwordx4 v179, s[98:99]
	v_mfma_f32_16x16x32_bf16 v[60:63], v[112:115], v[96:99], v[60:63]
	v_mfma_f32_16x16x32_bf16 v[56:59], v[116:119], v[96:99], v[56:59]
	v_mfma_f32_16x16x32_bf16 v[52:55], v[120:123], v[96:99], v[52:55]
	v_mfma_f32_16x16x32_bf16 v[48:51], v[124:127], v[96:99], v[48:51]
	v_mfma_f32_16x16x32_bf16 v[44:47], v[112:115], v[100:103], v[44:47]
	v_mfma_f32_16x16x32_bf16 v[40:43], v[116:119], v[100:103], v[40:43]
	v_mfma_f32_16x16x32_bf16 v[36:39], v[120:123], v[100:103], v[36:39]
	v_mfma_f32_16x16x32_bf16 v[24:27], v[124:127], v[100:103], v[24:27]
	v_mov_b32_e32 v150, v178
	s_add_i32 m0, s13, 0x800
	s_add_u32 s100, s20, s76
	s_addc_u32 s101, s21, s77
	global_load_lds_dwordx4 v178, s[100:101]
	s_add_i32 s13, s10, 1
	v_mfma_f32_16x16x32_bf16 v[20:23], v[112:115], v[104:107], v[20:23]
	s_cmp_lg_u32 s10, 2
	s_cselect_b32 s10, s13, 0
	s_add_u32 s4, s4, 0x80
	v_mfma_f32_16x16x32_bf16 v[16:19], v[116:119], v[104:107], v[16:19]
	s_addc_u32 s5, s5, 0
	s_cmpk_eq_i32 s4, 0x680
	v_mfma_f32_16x16x32_bf16 v[12:15], v[120:123], v[104:107], v[12:15]
	v_mfma_f32_16x16x32_bf16 v[8:11], v[124:127], v[104:107], v[8:11]
	v_mfma_f32_16x16x32_bf16 v[4:7], v[112:115], v[108:111], v[4:7]
	v_mfma_f32_16x16x32_bf16 v[0:3], v[116:119], v[108:111], v[0:3]
	v_mfma_f32_16x16x32_bf16 v[28:31], v[120:123], v[108:111], v[28:31]
	v_mfma_f32_16x16x32_bf16 v[32:35], v[124:127], v[108:111], v[32:35]
	s_cbranch_scc0 .LBB0_667
	s_waitcnt vmcnt(6) lgkmcnt(0)
	s_barrier
	s_mul_i32 s4, s10, 0xc000
	s_add_i32 s4, s4, 0
	v_add_u32_e32 v64, s4, v157
	v_add3_u32 v65, v64, s18, v169
	v_add3_u32 v64, v64, s17, v169
	v_add_u32_e32 v68, s4, v158
	ds_read_b128 v[124:127], v65
	ds_read_b128 v[120:123], v65 offset:2048
	ds_read_b128 v[100:103], v65 offset:4096
	ds_read_b128 v[96:99], v65 offset:6144
	ds_read_b128 v[108:111], v64 offset:32768
	ds_read_b128 v[112:115], v64 offset:34816
	ds_read_b128 v[116:119], v64 offset:36864
	ds_read_b128 v[104:107], v64 offset:38912
	v_add3_u32 v64, v68, s18, v169
	v_add3_u32 v68, v68, s17, v169
	ds_read_b128 v[92:95], v64
	ds_read_b128 v[88:91], v64 offset:2048
	ds_read_b128 v[72:75], v64 offset:4096
	ds_read_b128 v[64:67], v64 offset:6144
	ds_read_b128 v[76:79], v68 offset:32768
	ds_read_b128 v[80:83], v68 offset:34816
	ds_read_b128 v[84:87], v68 offset:36864
	ds_read_b128 v[68:71], v68 offset:38912
	s_waitcnt lgkmcnt(0)
	v_sub_co_u32_e64 v128, s[4:5], s10, 1
	s_and_b64 s[4:5], s[4:5], exec
	v_readfirstlane_b32 s4, v128
	s_cselect_b32 s13, 2, s4
	v_cndmask_b32_e64 v128, 0, 1, s[90:91]
	s_mov_b64 s[4:5], -1
	v_cmp_ne_u32_e64 s[6:7], 1, v128
	s_andn2_b64 vcc, exec, s[90:91]
	s_mul_i32 s12, s13, 0xc000
	s_cbranch_vccnz .LBB0_670
	s_mul_i32 s11, s13, 0xc000
	s_mov_b64 s[4:5], 0

.LBB0_756:
	s_waitcnt vmcnt(6) lgkmcnt(0)
	s_barrier
	s_waitcnt lgkmcnt(0)
	v_mfma_f32_16x16x32_bf16 v[124:127], v[52:55], v[64:67], v[124:127]
	s_mul_i32 s19, s96, 0xc000
	s_add_i32 s24, s19, 0xffff4000
	v_mfma_f32_16x16x32_bf16 v[120:123], v[48:51], v[64:67], v[120:123]
	s_cmp_lg_u32 s96, 0
	s_cselect_b32 s24, s24, 0x18000
	s_add_i32 vcc_hi, s5, s24
	v_mfma_f32_16x16x32_bf16 v[116:119], v[44:47], v[64:67], v[116:119]
	v_mfma_f32_16x16x32_bf16 v[64:67], v[40:43], v[64:67], v[112:115]
	v_mfma_f32_16x16x32_bf16 v[108:111], v[52:55], v[56:59], v[108:111]
	v_mfma_f32_16x16x32_bf16 v[104:107], v[48:51], v[56:59], v[104:107]
	v_mfma_f32_16x16x32_bf16 v[100:103], v[44:47], v[56:59], v[100:103]
	v_mfma_f32_16x16x32_bf16 v[56:59], v[40:43], v[56:59], v[96:99]
	s_add_u32 s26, s10, s8
	v_mov_b32_e32 v150, v164
	s_addc_u32 s27, s11, s9
	s_mov_b64 s[60:61], 0x4400180
	s_mov_b32 m0, vcc_hi
	s_nop 0
	s_add_u32 s98, s26, 0x4400180
	s_addc_u32 s99, s27, 0x0
	global_load_lds_dwordx4 v164, s[98:99]
	v_mfma_f32_16x16x32_bf16 v[92:95], v[52:55], v[36:39], v[92:95]
	v_mfma_f32_16x16x32_bf16 v[88:91], v[48:51], v[36:39], v[88:91]
	v_mfma_f32_16x16x32_bf16 v[84:87], v[44:47], v[36:39], v[84:87]
	v_mfma_f32_16x16x32_bf16 v[36:39], v[40:43], v[36:39], v[80:83]
	v_mfma_f32_16x16x32_bf16 v[52:55], v[52:55], v[32:35], v[76:79]
	v_mfma_f32_16x16x32_bf16 v[48:51], v[48:51], v[32:35], v[72:75]
	v_mfma_f32_16x16x32_bf16 v[44:47], v[44:47], v[32:35], v[68:71]
	v_mfma_f32_16x16x32_bf16 v[32:35], v[40:43], v[32:35], v[60:63]
	v_mov_b32_e32 v150, v165
	s_mov_b64 s[60:61], 0x440b180
	s_add_i32 m0, vcc_hi, 0x400
	s_nop 0
	s_add_u32 s100, s26, 0x440b180
	s_addc_u32 s101, s27, 0x0
	global_load_lds_dwordx4 v165, s[100:101]
	v_mfma_f32_16x16x32_bf16 v[124:127], v[20:23], v[28:31], v[124:127]
	v_mfma_f32_16x16x32_bf16 v[120:123], v[16:19], v[28:31], v[120:123]
	v_mfma_f32_16x16x32_bf16 v[116:119], v[12:15], v[28:31], v[116:119]
	v_mfma_f32_16x16x32_bf16 v[112:115], v[8:11], v[28:31], v[64:67]
	v_mfma_f32_16x16x32_bf16 v[108:111], v[20:23], v[24:27], v[108:111]
	v_mfma_f32_16x16x32_bf16 v[104:107], v[16:19], v[24:27], v[104:107]
	v_mfma_f32_16x16x32_bf16 v[100:103], v[12:15], v[24:27], v[100:103]
	v_mfma_f32_16x16x32_bf16 v[96:99], v[8:11], v[24:27], v[56:59]
	v_mov_b32_e32 v150, v164
	s_mov_b64 s[60:61], 0x4416180
	s_add_i32 m0, vcc_hi, 0x800
	s_nop 0
	s_add_u32 s98, s26, 0x4416180
	s_addc_u32 s99, s27, 0x0
	global_load_lds_dwordx4 v164, s[98:99]
	v_mfma_f32_16x16x32_bf16 v[92:95], v[20:23], v[4:7], v[92:95]
	s_waitcnt lgkmcnt(0)
	v_mfma_f32_16x16x32_bf16 v[88:91], v[16:19], v[4:7], v[88:91]
	v_mfma_f32_16x16x32_bf16 v[84:87], v[12:15], v[4:7], v[84:87]
	v_mfma_f32_16x16x32_bf16 v[80:83], v[8:11], v[4:7], v[36:39]
	v_mfma_f32_16x16x32_bf16 v[76:79], v[20:23], v[0:3], v[52:55]
	v_mfma_f32_16x16x32_bf16 v[72:75], v[16:19], v[0:3], v[48:51]
	v_mfma_f32_16x16x32_bf16 v[68:71], v[12:15], v[0:3], v[44:47]
	v_mfma_f32_16x16x32_bf16 v[60:63], v[8:11], v[0:3], v[32:35]
	s_barrier
	s_add_i32 s19, s19, 0
	v_add_u32_e32 v0, s19, v155
	v_add3_u32 v1, v0, s18, v169
	v_add3_u32 v0, v0, s17, v169
	v_add_u32_e32 v8, s19, v156
	ds_read_b128 v[64:67], v1
	ds_read_b128 v[56:59], v1 offset:2048
	ds_read_b128 v[36:39], v1 offset:4096
	ds_read_b128 v[32:35], v1 offset:6144
	ds_read_b128 v[52:55], v0 offset:32768
	ds_read_b128 v[48:51], v0 offset:34816
	ds_read_b128 v[44:47], v0 offset:36864
	ds_read_b128 v[40:43], v0 offset:38912
	v_add3_u32 v0, v8, s18, v169
	v_add3_u32 v8, v8, s17, v169
	ds_read_b128 v[28:31], v0
	ds_read_b128 v[24:27], v0 offset:2048
	ds_read_b128 v[4:7], v0 offset:4096
	ds_read_b128 v[0:3], v0 offset:6144
	ds_read_b128 v[20:23], v8 offset:32768
	ds_read_b128 v[16:19], v8 offset:34816
	ds_read_b128 v[12:15], v8 offset:36864
	ds_read_b128 v[8:11], v8 offset:38912
	s_waitcnt lgkmcnt(0)
	s_add_i32 s19, s24, 0
	v_mov_b32_e32 v150, v165
	s_add_i32 s24, s19, s4
	s_add_i32 m0, s24, 0xc00
	s_add_u32 s100, s26, 0x4421180
	s_addc_u32 s101, s27, 0x0
	s_mov_b64 s[26:27], 0x4421180
	s_add_u32 s26, s97, s8
	v_mov_b32_e32 v150, v164
	s_addc_u32 s27, vcc_lo, s9
	global_load_lds_dwordx4 v165, s[100:101]
	s_mov_b64 s[60:61], 0x1400180
	s_add_i32 s19, s19, s16
	s_add_i32 m0, s19, 0x8000
	v_mov_b32_e32 v150, v165
	s_add_u32 s98, s26, 0x1400180
	s_addc_u32 s99, s27, 0x0
	global_load_lds_dwordx4 v164, s[98:99]
	s_add_i32 m0, s19, 0x8400
	s_add_u32 s100, s26, 0x140b180
	s_addc_u32 s101, s27, 0x0
	s_mov_b64 s[26:27], 0x140b180
	global_load_lds_dwordx4 v165, s[100:101]
	s_add_i32 s19, s96, 1
	s_cmp_lg_u32 s96, 2
	s_cselect_b32 s96, s19, 0
	s_add_u32 s8, s8, 0x80
	s_addc_u32 s9, s9, 0
	s_cmpk_eq_i32 s8, 0x1480
	s_cbranch_scc0 .LBB0_756
	s_waitcnt vmcnt(6) lgkmcnt(0)
	s_barrier
	s_waitcnt lgkmcnt(0)
	v_mfma_f32_16x16x32_bf16 v[124:127], v[52:55], v[64:67], v[124:127]
	s_mul_i32 s11, s96, 0xc000
	s_add_i32 s8, s11, 0xffff4000
	v_mfma_f32_16x16x32_bf16 v[120:123], v[48:51], v[64:67], v[120:123]
	s_cmp_lg_u32 s96, 0
	s_cselect_b32 s10, s8, 0x18000
	s_andn2_b64 vcc, exec, s[12:13]
	v_mfma_f32_16x16x32_bf16 v[116:119], v[44:47], v[64:67], v[116:119]
	v_mfma_f32_16x16x32_bf16 v[64:67], v[40:43], v[64:67], v[112:115]
	v_mfma_f32_16x16x32_bf16 v[108:111], v[52:55], v[56:59], v[108:111]
	s_nop 1
	v_cndmask_b32_e64 v112, 0, 1, s[12:13]
	v_cmp_ne_u32_e64 s[8:9], 1, v112
	v_mfma_f32_16x16x32_bf16 v[104:107], v[48:51], v[56:59], v[104:107]
	v_mfma_f32_16x16x32_bf16 v[100:103], v[44:47], v[56:59], v[100:103]
	v_mfma_f32_16x16x32_bf16 v[140:143], v[40:43], v[56:59], v[96:99]
	s_cbranch_vccnz .LBB0_759
	s_add_u32 s26, s83, s14
	v_mov_b32_e32 v56, v164
	s_addc_u32 s27, s89, s15
	s_add_i32 m0, s5, s10
	s_nop 0
	global_load_lds_dwordx4 v56, s[26:27]

.LBB0_952:
	s_waitcnt vmcnt(6) lgkmcnt(0)
	s_barrier
	s_waitcnt lgkmcnt(0)
	v_mfma_f32_16x16x32_bf16 v[124:127], v[52:55], v[64:67], v[124:127]
	s_mul_i32 s48, s97, 0xc000
	s_add_i32 s16, s48, 0xffff4000
	v_mfma_f32_16x16x32_bf16 v[120:123], v[48:51], v[64:67], v[120:123]
	s_cmp_lg_u32 s97, 0
	s_cselect_b32 s49, s16, 0x18000
	s_add_i32 s2, s61, s49
	v_mfma_f32_16x16x32_bf16 v[116:119], v[44:47], v[64:67], v[116:119]
	v_mfma_f32_16x16x32_bf16 v[64:67], v[40:43], v[64:67], v[112:115]
	v_mfma_f32_16x16x32_bf16 v[108:111], v[52:55], v[56:59], v[108:111]
	v_mfma_f32_16x16x32_bf16 v[104:107], v[48:51], v[56:59], v[104:107]
	v_mfma_f32_16x16x32_bf16 v[100:103], v[44:47], v[56:59], v[100:103]
	v_mfma_f32_16x16x32_bf16 v[56:59], v[40:43], v[56:59], v[96:99]
	s_add_u32 s16, s10, s8
	v_mov_b32_e32 v150, v178
	s_addc_u32 s17, s11, s9
	s_mov_b32 m0, s2
	s_add_u32 s98, s16, s74
	s_addc_u32 s99, s17, s75
	global_load_lds_dwordx4 v178, s[98:99]
	v_mfma_f32_16x16x32_bf16 v[92:95], v[52:55], v[36:39], v[92:95]
	v_mfma_f32_16x16x32_bf16 v[88:91], v[48:51], v[36:39], v[88:91]
	v_mfma_f32_16x16x32_bf16 v[84:87], v[44:47], v[36:39], v[84:87]
	v_mfma_f32_16x16x32_bf16 v[36:39], v[40:43], v[36:39], v[80:83]
	v_mfma_f32_16x16x32_bf16 v[52:55], v[52:55], v[32:35], v[76:79]
	v_mfma_f32_16x16x32_bf16 v[48:51], v[48:51], v[32:35], v[72:75]
	v_mfma_f32_16x16x32_bf16 v[44:47], v[44:47], v[32:35], v[68:71]
	v_mfma_f32_16x16x32_bf16 v[32:35], v[40:43], v[32:35], v[60:63]
	v_mov_b32_e32 v150, v179
	s_add_i32 m0, s2, 0x400
	s_add_u32 s100, s16, s76
	s_addc_u32 s101, s17, s77
	global_load_lds_dwordx4 v179, s[100:101]
	v_mfma_f32_16x16x32_bf16 v[124:127], v[20:23], v[28:31], v[124:127]
	v_mfma_f32_16x16x32_bf16 v[120:123], v[16:19], v[28:31], v[120:123]
	v_mfma_f32_16x16x32_bf16 v[116:119], v[12:15], v[28:31], v[116:119]
	v_mfma_f32_16x16x32_bf16 v[112:115], v[8:11], v[28:31], v[64:67]
	v_mfma_f32_16x16x32_bf16 v[108:111], v[20:23], v[24:27], v[108:111]
	v_mfma_f32_16x16x32_bf16 v[104:107], v[16:19], v[24:27], v[104:107]
	v_mfma_f32_16x16x32_bf16 v[100:103], v[12:15], v[24:27], v[100:103]
	v_mfma_f32_16x16x32_bf16 v[96:99], v[8:11], v[24:27], v[56:59]
	v_mov_b32_e32 v150, v178
	s_add_i32 m0, s2, 0x800
	s_add_u32 s98, s16, s78
	s_addc_u32 s99, s17, s79
	global_load_lds_dwordx4 v178, s[98:99]
	v_mfma_f32_16x16x32_bf16 v[92:95], v[20:23], v[4:7], v[92:95]
	s_waitcnt lgkmcnt(0)
	v_mfma_f32_16x16x32_bf16 v[88:91], v[16:19], v[4:7], v[88:91]
	v_mfma_f32_16x16x32_bf16 v[84:87], v[12:15], v[4:7], v[84:87]
	v_mfma_f32_16x16x32_bf16 v[80:83], v[8:11], v[4:7], v[36:39]
	v_mfma_f32_16x16x32_bf16 v[76:79], v[20:23], v[0:3], v[52:55]
	v_mfma_f32_16x16x32_bf16 v[72:75], v[16:19], v[0:3], v[48:51]
	v_mfma_f32_16x16x32_bf16 v[68:71], v[12:15], v[0:3], v[44:47]
	v_mfma_f32_16x16x32_bf16 v[60:63], v[8:11], v[0:3], v[32:35]
	s_barrier
	s_add_i32 s2, s48, 0
	v_add_u32_e32 v0, s2, v186
	v_add3_u32 v1, v0, s66, v169
	v_add3_u32 v0, v0, s65, v169
	v_add_u32_e32 v8, s2, v187
	ds_read_b128 v[64:67], v1
	ds_read_b128 v[56:59], v1 offset:2048
	ds_read_b128 v[36:39], v1 offset:4096
	ds_read_b128 v[32:35], v1 offset:6144
	ds_read_b128 v[52:55], v0 offset:32768
	ds_read_b128 v[48:51], v0 offset:34816
	ds_read_b128 v[44:47], v0 offset:36864
	ds_read_b128 v[40:43], v0 offset:38912
	v_add3_u32 v0, v8, s66, v169
	v_add3_u32 v8, v8, s65, v169
	ds_read_b128 v[28:31], v0
	ds_read_b128 v[24:27], v0 offset:2048
	ds_read_b128 v[4:7], v0 offset:4096
	ds_read_b128 v[0:3], v0 offset:6144
	ds_read_b128 v[20:23], v8 offset:32768
	ds_read_b128 v[16:19], v8 offset:34816
	ds_read_b128 v[12:15], v8 offset:36864
	ds_read_b128 v[8:11], v8 offset:38912
	s_waitcnt lgkmcnt(0)
	s_add_i32 s2, s49, 0
	v_mov_b32_e32 v150, v179
	s_nop 0
	s_add_u32 s100, s16, s80
	s_addc_u32 s101, s17, s81
	s_add_i32 s16, s2, s60
	s_add_i32 m0, s16, 0xc00
	s_add_u32 s16, vcc_lo, s8
	v_mov_b32_e32 v150, v178
	s_addc_u32 s17, vcc_hi, s9
	global_load_lds_dwordx4 v179, s[100:101]
	s_add_i32 s2, s2, s62
	s_add_i32 m0, s2, 0x8000
	v_mov_b32_e32 v150, v179
	s_add_u32 s98, s16, s82
	s_addc_u32 s99, s17, s83
	global_load_lds_dwordx4 v178, s[98:99]
	s_add_i32 m0, s2, 0x8400
	s_add_u32 s100, s16, s84
	s_addc_u32 s101, s17, s85
	global_load_lds_dwordx4 v179, s[100:101]
	s_add_i32 s2, s97, 1
	s_cmp_lg_u32 s97, 2
	s_cselect_b32 s97, s2, 0
	s_add_u32 s8, s8, 0x80
	s_addc_u32 s9, s9, 0
	s_cmpk_eq_i32 s8, 0x680
	s_cbranch_scc0 .LBB0_952
	s_waitcnt vmcnt(6) lgkmcnt(0)
	s_barrier
	s_waitcnt lgkmcnt(0)
	v_mfma_f32_16x16x32_bf16 v[124:127], v[52:55], v[64:67], v[124:127]
	s_mul_i32 s11, s97, 0xc000
	s_add_i32 s8, s11, 0xffff4000
	v_mfma_f32_16x16x32_bf16 v[120:123], v[48:51], v[64:67], v[120:123]
	s_cmp_lg_u32 s97, 0
	s_cselect_b32 s10, s8, 0x18000
	s_andn2_b64 vcc, exec, s[12:13]
	v_mfma_f32_16x16x32_bf16 v[116:119], v[44:47], v[64:67], v[116:119]
	v_mfma_f32_16x16x32_bf16 v[64:67], v[40:43], v[64:67], v[112:115]
	v_mfma_f32_16x16x32_bf16 v[108:111], v[52:55], v[56:59], v[108:111]
	s_nop 1
	v_cndmask_b32_e64 v112, 0, 1, s[12:13]
	v_cmp_ne_u32_e64 s[8:9], 1, v112
	v_mfma_f32_16x16x32_bf16 v[104:107], v[48:51], v[56:59], v[104:107]
	v_mfma_f32_16x16x32_bf16 v[100:103], v[44:47], v[56:59], v[100:103]
	v_mfma_f32_16x16x32_bf16 v[140:143], v[40:43], v[56:59], v[96:99]
	s_cbranch_vccnz .LBB0_955
	s_add_u32 s16, s24, s14
	v_mov_b32_e32 v56, v178
	s_addc_u32 s17, s25, s15
	s_add_i32 m0, s61, s10
	s_nop 0
	global_load_lds_dwordx4 v56, s[16:17]

.LBB0_979:
	s_waitcnt vmcnt(6) lgkmcnt(0)
	s_barrier
	s_mul_i32 s16, s10, 0xc000
	s_add_i32 s17, s16, 0
	v_add_u32_e32 v80, s17, v186
	v_add_u32_e32 v112, s17, v187
	v_add3_u32 v76, v80, s66, v169
	v_add3_u32 v92, v80, s65, v169
	v_add3_u32 v108, v112, s66, v169
	v_add3_u32 v124, v112, s65, v169
	ds_read_b128 v[64:67], v76
	ds_read_b128 v[68:71], v76 offset:2048
	ds_read_b128 v[72:75], v76 offset:4096
	ds_read_b128 v[76:79], v76 offset:6144
	ds_read_b128 v[80:83], v92 offset:32768
	ds_read_b128 v[84:87], v92 offset:34816
	ds_read_b128 v[88:91], v92 offset:36864
	ds_read_b128 v[92:95], v92 offset:38912
	ds_read_b128 v[96:99], v108
	ds_read_b128 v[100:103], v108 offset:2048
	ds_read_b128 v[104:107], v108 offset:4096
	ds_read_b128 v[108:111], v108 offset:6144
	ds_read_b128 v[112:115], v124 offset:32768
	ds_read_b128 v[116:119], v124 offset:34816
	ds_read_b128 v[120:123], v124 offset:36864
	ds_read_b128 v[124:127], v124 offset:38912
	s_waitcnt lgkmcnt(0)
	s_add_i32 s16, s16, 0xffff4000
	s_cmp_lg_u32 s10, 0
	s_cselect_b32 s23, s16, 0x18000
	s_add_i32 s48, s23, 0
	s_add_u32 s16, s8, s6
	s_addc_u32 s17, s9, s7
	s_add_i32 s26, s48, s60
	v_mov_b32_e32 v150, v179
	s_add_i32 m0, s26, 0xc00
	s_add_u32 s26, s11, s6
	v_mov_b32_e32 v150, v178
	s_addc_u32 s27, s22, s7
	s_add_u32 s98, s16, s80
	s_addc_u32 s99, s17, s81
	global_load_lds_dwordx4 v179, s[98:99]
	s_add_i32 s48, s48, s62
	s_add_i32 m0, s48, 0x8000
	v_mov_b32_e32 v150, v179
	s_add_u32 s100, s26, s82
	s_addc_u32 s101, s27, s83
	global_load_lds_dwordx4 v178, s[100:101]
	s_add_i32 m0, s48, 0x8400
	s_add_u32 s98, s26, s84
	s_addc_u32 s99, s27, s85
	global_load_lds_dwordx4 v179, s[98:99]
	s_waitcnt lgkmcnt(0)
	s_barrier
	s_waitcnt lgkmcnt(0)
	v_mfma_f32_16x16x32_bf16 v[60:63], v[80:83], v[64:67], v[60:63]
	s_add_i32 s23, s61, s23
	v_mfma_f32_16x16x32_bf16 v[56:59], v[84:87], v[64:67], v[56:59]
	v_mfma_f32_16x16x32_bf16 v[52:55], v[88:91], v[64:67], v[52:55]
	v_mfma_f32_16x16x32_bf16 v[48:51], v[92:95], v[64:67], v[48:51]
	v_mfma_f32_16x16x32_bf16 v[44:47], v[80:83], v[68:71], v[44:47]
	v_mfma_f32_16x16x32_bf16 v[40:43], v[84:87], v[68:71], v[40:43]
	v_mfma_f32_16x16x32_bf16 v[36:39], v[88:91], v[68:71], v[36:39]
	v_mfma_f32_16x16x32_bf16 v[28:31], v[92:95], v[68:71], v[28:31]
	v_mov_b32_e32 v150, v178
	s_mov_b32 m0, s23
	s_add_u32 s100, s16, s74
	s_addc_u32 s101, s17, s75
	global_load_lds_dwordx4 v178, s[100:101]
	v_mfma_f32_16x16x32_bf16 v[24:27], v[80:83], v[72:75], v[24:27]
	v_mfma_f32_16x16x32_bf16 v[20:23], v[84:87], v[72:75], v[20:23]
	v_mfma_f32_16x16x32_bf16 v[16:19], v[88:91], v[72:75], v[16:19]
	v_mfma_f32_16x16x32_bf16 v[12:15], v[92:95], v[72:75], v[12:15]
	v_mfma_f32_16x16x32_bf16 v[8:11], v[80:83], v[76:79], v[8:11]
	v_mfma_f32_16x16x32_bf16 v[4:7], v[84:87], v[76:79], v[4:7]
	v_mfma_f32_16x16x32_bf16 v[0:3], v[88:91], v[76:79], v[0:3]
	v_mfma_f32_16x16x32_bf16 v[32:35], v[92:95], v[76:79], v[32:35]
	v_mov_b32_e32 v150, v179
	s_add_i32 m0, s23, 0x400
	s_add_u32 s98, s16, s76
	s_addc_u32 s99, s17, s77
	global_load_lds_dwordx4 v179, s[98:99]
	v_mfma_f32_16x16x32_bf16 v[60:63], v[112:115], v[96:99], v[60:63]
	v_mfma_f32_16x16x32_bf16 v[56:59], v[116:119], v[96:99], v[56:59]
	v_mfma_f32_16x16x32_bf16 v[52:55], v[120:123], v[96:99], v[52:55]
	v_mfma_f32_16x16x32_bf16 v[48:51], v[124:127], v[96:99], v[48:51]
	v_mfma_f32_16x16x32_bf16 v[44:47], v[112:115], v[100:103], v[44:47]
	v_mfma_f32_16x16x32_bf16 v[40:43], v[116:119], v[100:103], v[40:43]
	v_mfma_f32_16x16x32_bf16 v[36:39], v[120:123], v[100:103], v[36:39]
	v_mfma_f32_16x16x32_bf16 v[28:31], v[124:127], v[100:103], v[28:31]
	v_mov_b32_e32 v150, v178
	s_add_i32 m0, s23, 0x800
	s_add_u32 s100, s16, s78
	s_addc_u32 s101, s17, s79
	global_load_lds_dwordx4 v178, s[100:101]
	s_add_i32 s16, s10, 1
	v_mfma_f32_16x16x32_bf16 v[24:27], v[112:115], v[104:107], v[24:27]
	s_cmp_lg_u32 s10, 2
	s_cselect_b32 s10, s16, 0
	s_add_u32 s6, s6, 0x80
	v_mfma_f32_16x16x32_bf16 v[20:23], v[116:119], v[104:107], v[20:23]
	s_addc_u32 s7, s7, 0
	s_cmpk_eq_i32 s6, 0x680
	v_mfma_f32_16x16x32_bf16 v[16:19], v[120:123], v[104:107], v[16:19]
	v_mfma_f32_16x16x32_bf16 v[12:15], v[124:127], v[104:107], v[12:15]
	v_mfma_f32_16x16x32_bf16 v[8:11], v[112:115], v[108:111], v[8:11]
	v_mfma_f32_16x16x32_bf16 v[4:7], v[116:119], v[108:111], v[4:7]
	v_mfma_f32_16x16x32_bf16 v[0:3], v[120:123], v[108:111], v[0:3]
	v_mfma_f32_16x16x32_bf16 v[32:35], v[124:127], v[108:111], v[32:35]
	s_cbranch_scc0 .LBB0_979
	s_waitcnt vmcnt(6) lgkmcnt(0)
	s_barrier
	s_mul_i32 s2, s10, 0xc000
	s_add_i32 s2, s2, 0
	v_add_u32_e32 v64, s2, v186
	v_add3_u32 v65, v64, s66, v169
	v_add3_u32 v64, v64, s65, v169
	v_add_u32_e32 v68, s2, v187
	ds_read_b128 v[124:127], v65
	ds_read_b128 v[120:123], v65 offset:2048
	ds_read_b128 v[100:103], v65 offset:4096
	ds_read_b128 v[96:99], v65 offset:6144
	ds_read_b128 v[108:111], v64 offset:32768
	ds_read_b128 v[112:115], v64 offset:34816
	ds_read_b128 v[116:119], v64 offset:36864
	ds_read_b128 v[104:107], v64 offset:38912
	v_add3_u32 v64, v68, s66, v169
	v_add3_u32 v68, v68, s65, v169
	ds_read_b128 v[92:95], v64
	ds_read_b128 v[88:91], v64 offset:2048
	ds_read_b128 v[72:75], v64 offset:4096
	ds_read_b128 v[64:67], v64 offset:6144
	ds_read_b128 v[76:79], v68 offset:32768
	ds_read_b128 v[80:83], v68 offset:34816
	ds_read_b128 v[84:87], v68 offset:36864
	ds_read_b128 v[68:71], v68 offset:38912
	s_waitcnt lgkmcnt(0)
	v_sub_co_u32_e64 v128, s[6:7], s10, 1
	s_and_b64 s[6:7], s[6:7], exec
	v_readfirstlane_b32 s2, v128
	s_cselect_b32 s23, 2, s2
	v_cndmask_b32_e64 v128, 0, 1, s[94:95]
	s_mov_b64 s[6:7], -1
	v_cmp_ne_u32_e64 s[8:9], 1, v128
	s_andn2_b64 vcc, exec, s[94:95]
	s_mul_i32 s22, s23, 0xc000
	s_cbranch_vccnz .LBB0_982
	s_mul_i32 s11, s23, 0xc000
	s_mov_b64 s[6:7], 0

.LBB0_1183:
	s_waitcnt vmcnt(6) lgkmcnt(0)
	s_barrier
	s_waitcnt lgkmcnt(0)
	v_mfma_f32_16x16x32_bf16 v[124:127], v[52:55], v[64:67], v[124:127]
	s_mul_i32 s76, s97, 0xc000
	s_add_i32 s16, s76, 0xffff4000
	v_mfma_f32_16x16x32_bf16 v[120:123], v[48:51], v[64:67], v[120:123]
	s_cmp_lg_u32 s97, 0
	s_cselect_b32 s77, s16, 0x18000
	s_add_i32 s33, s4, s77
	v_mfma_f32_16x16x32_bf16 v[116:119], v[44:47], v[64:67], v[116:119]
	v_mfma_f32_16x16x32_bf16 v[64:67], v[40:43], v[64:67], v[112:115]
	v_mfma_f32_16x16x32_bf16 v[108:111], v[52:55], v[56:59], v[108:111]
	v_mfma_f32_16x16x32_bf16 v[104:107], v[48:51], v[56:59], v[104:107]
	v_mfma_f32_16x16x32_bf16 v[100:103], v[44:47], v[56:59], v[100:103]
	v_mfma_f32_16x16x32_bf16 v[56:59], v[40:43], v[56:59], v[96:99]
	s_add_u32 s16, s10, s8
	v_mov_b32_e32 v148, v162
	s_addc_u32 s17, s11, s9
	s_mov_b32 m0, s33
	s_add_u32 s98, s16, s38
	s_addc_u32 s99, s17, s39
	global_load_lds_dwordx4 v162, s[98:99]
	v_mfma_f32_16x16x32_bf16 v[92:95], v[52:55], v[36:39], v[92:95]
	v_mfma_f32_16x16x32_bf16 v[88:91], v[48:51], v[36:39], v[88:91]
	v_mfma_f32_16x16x32_bf16 v[84:87], v[44:47], v[36:39], v[84:87]
	v_mfma_f32_16x16x32_bf16 v[36:39], v[40:43], v[36:39], v[80:83]
	v_mfma_f32_16x16x32_bf16 v[52:55], v[52:55], v[32:35], v[76:79]
	v_mfma_f32_16x16x32_bf16 v[48:51], v[48:51], v[32:35], v[72:75]
	v_mfma_f32_16x16x32_bf16 v[44:47], v[44:47], v[32:35], v[68:71]
	v_mfma_f32_16x16x32_bf16 v[32:35], v[40:43], v[32:35], v[60:63]
	v_mov_b32_e32 v148, v163
	s_add_i32 m0, s33, 0x400
	s_add_u32 s100, s16, s40
	s_addc_u32 s101, s17, s41
	global_load_lds_dwordx4 v163, s[100:101]
	v_mfma_f32_16x16x32_bf16 v[124:127], v[20:23], v[28:31], v[124:127]
	v_mfma_f32_16x16x32_bf16 v[120:123], v[16:19], v[28:31], v[120:123]
	v_mfma_f32_16x16x32_bf16 v[116:119], v[12:15], v[28:31], v[116:119]
	v_mfma_f32_16x16x32_bf16 v[112:115], v[8:11], v[28:31], v[64:67]
	v_mfma_f32_16x16x32_bf16 v[108:111], v[20:23], v[24:27], v[108:111]
	v_mfma_f32_16x16x32_bf16 v[104:107], v[16:19], v[24:27], v[104:107]
	v_mfma_f32_16x16x32_bf16 v[100:103], v[12:15], v[24:27], v[100:103]
	v_mfma_f32_16x16x32_bf16 v[96:99], v[8:11], v[24:27], v[56:59]
	v_mov_b32_e32 v148, v162
	s_add_i32 m0, s33, 0x800
	s_add_u32 s98, s16, s42
	s_addc_u32 s99, s17, s43
	global_load_lds_dwordx4 v162, s[98:99]
	v_mfma_f32_16x16x32_bf16 v[92:95], v[20:23], v[4:7], v[92:95]
	s_waitcnt lgkmcnt(0)
	v_mfma_f32_16x16x32_bf16 v[88:91], v[16:19], v[4:7], v[88:91]
	v_mfma_f32_16x16x32_bf16 v[84:87], v[12:15], v[4:7], v[84:87]
	v_mfma_f32_16x16x32_bf16 v[80:83], v[8:11], v[4:7], v[36:39]
	v_mfma_f32_16x16x32_bf16 v[76:79], v[20:23], v[0:3], v[52:55]
	v_mfma_f32_16x16x32_bf16 v[72:75], v[16:19], v[0:3], v[48:51]
	v_mfma_f32_16x16x32_bf16 v[68:71], v[12:15], v[0:3], v[44:47]
	v_mfma_f32_16x16x32_bf16 v[60:63], v[8:11], v[0:3], v[32:35]
	s_barrier
	s_add_i32 s33, s76, 0
	v_add_u32_e32 v0, s33, v153
	v_add3_u32 v1, v0, s29, v169
	v_add3_u32 v0, v0, s28, v169
	v_add_u32_e32 v8, s33, v154
	ds_read_b128 v[64:67], v1
	ds_read_b128 v[56:59], v1 offset:2048
	ds_read_b128 v[36:39], v1 offset:4096
	ds_read_b128 v[32:35], v1 offset:6144
	ds_read_b128 v[52:55], v0 offset:32768
	ds_read_b128 v[48:51], v0 offset:34816
	ds_read_b128 v[44:47], v0 offset:36864
	ds_read_b128 v[40:43], v0 offset:38912
	v_add3_u32 v0, v8, s29, v169
	v_add3_u32 v8, v8, s28, v169
	ds_read_b128 v[28:31], v0
	ds_read_b128 v[24:27], v0 offset:2048
	ds_read_b128 v[4:7], v0 offset:4096
	ds_read_b128 v[0:3], v0 offset:6144
	ds_read_b128 v[20:23], v8 offset:32768
	ds_read_b128 v[16:19], v8 offset:34816
	ds_read_b128 v[12:15], v8 offset:36864
	ds_read_b128 v[8:11], v8 offset:38912
	s_waitcnt lgkmcnt(0)
	s_add_i32 s33, s77, 0
	v_mov_b32_e32 v148, v163
	s_nop 0
	s_add_u32 s100, s16, s44
	s_addc_u32 s101, s17, s45
	s_add_i32 s16, s33, s3
	s_add_i32 m0, s16, 0xc00
	s_add_u32 s16, vcc_lo, s8
	v_mov_b32_e32 v148, v162
	s_addc_u32 s17, vcc_hi, s9
	global_load_lds_dwordx4 v163, s[100:101]
	s_add_i32 s33, s33, s5
	s_add_i32 m0, s33, 0x8000
	v_mov_b32_e32 v148, v163
	s_add_u32 s98, s16, s46
	s_addc_u32 s99, s17, s47
	global_load_lds_dwordx4 v162, s[98:99]
	s_add_i32 m0, s33, 0x8400
	s_add_u32 s100, s16, s48
	s_addc_u32 s101, s17, s49
	global_load_lds_dwordx4 v163, s[100:101]
	s_add_i32 s16, s97, 1
	s_cmp_lg_u32 s97, 2
	s_cselect_b32 s97, s16, 0
	s_add_u32 s8, s8, 0x80
	s_addc_u32 s9, s9, 0
	s_cmpk_eq_i32 s8, 0x680
	s_cbranch_scc0 .LBB0_1183
	s_waitcnt vmcnt(6) lgkmcnt(0)
	s_barrier
	s_waitcnt lgkmcnt(0)
	v_mfma_f32_16x16x32_bf16 v[124:127], v[52:55], v[64:67], v[124:127]
	s_mul_i32 s11, s97, 0xc000
	s_add_i32 s8, s11, 0xffff4000
	v_mfma_f32_16x16x32_bf16 v[120:123], v[48:51], v[64:67], v[120:123]
	s_cmp_lg_u32 s97, 0
	s_cselect_b32 s10, s8, 0x18000
	s_andn2_b64 vcc, exec, s[70:71]
	v_mfma_f32_16x16x32_bf16 v[116:119], v[44:47], v[64:67], v[116:119]
	v_mfma_f32_16x16x32_bf16 v[64:67], v[40:43], v[64:67], v[112:115]
	v_mfma_f32_16x16x32_bf16 v[108:111], v[52:55], v[56:59], v[108:111]
	s_nop 1
	v_cndmask_b32_e64 v112, 0, 1, s[70:71]
	v_cmp_ne_u32_e64 s[8:9], 1, v112
	v_mfma_f32_16x16x32_bf16 v[104:107], v[48:51], v[56:59], v[104:107]
	v_mfma_f32_16x16x32_bf16 v[100:103], v[44:47], v[56:59], v[100:103]
	v_mfma_f32_16x16x32_bf16 v[140:143], v[40:43], v[56:59], v[96:99]
	s_cbranch_vccnz .LBB0_1186
	s_add_u32 s16, s89, s74
	v_mov_b32_e32 v56, v162
	s_addc_u32 s17, s90, s75
	s_add_i32 m0, s4, s10
	s_nop 0
	global_load_lds_dwordx4 v56, s[16:17]

.LBB0_1210:
	s_waitcnt vmcnt(6) lgkmcnt(0)
	s_barrier
	s_mul_i32 s16, s73, 0xc000
	s_add_i32 s17, s16, 0
	v_add_u32_e32 v80, s17, v153
	v_add_u32_e32 v112, s17, v154
	v_add3_u32 v76, v80, s29, v169
	v_add3_u32 v92, v80, s28, v169
	v_add3_u32 v108, v112, s29, v169
	v_add3_u32 v124, v112, s28, v169
	ds_read_b128 v[64:67], v76
	ds_read_b128 v[68:71], v76 offset:2048
	ds_read_b128 v[72:75], v76 offset:4096
	ds_read_b128 v[76:79], v76 offset:6144
	ds_read_b128 v[80:83], v92 offset:32768
	ds_read_b128 v[84:87], v92 offset:34816
	ds_read_b128 v[88:91], v92 offset:36864
	ds_read_b128 v[92:95], v92 offset:38912
	ds_read_b128 v[96:99], v108
	ds_read_b128 v[100:103], v108 offset:2048
	ds_read_b128 v[104:107], v108 offset:4096
	ds_read_b128 v[108:111], v108 offset:6144
	ds_read_b128 v[112:115], v124 offset:32768
	ds_read_b128 v[116:119], v124 offset:34816
	ds_read_b128 v[120:123], v124 offset:36864
	ds_read_b128 v[124:127], v124 offset:38912
	s_waitcnt lgkmcnt(0)
	s_add_i32 s16, s16, 0xffff4000
	s_cmp_lg_u32 s73, 0
	s_cselect_b32 s91, s16, 0x18000
	s_add_i32 s92, s91, 0
	s_add_u32 s16, s8, s6
	s_addc_u32 s17, s9, s7
	s_add_i32 s76, s92, s3
	v_mov_b32_e32 v148, v163
	s_add_i32 m0, s76, 0xc00
	s_add_u32 s76, s22, s6
	v_mov_b32_e32 v148, v162
	s_addc_u32 s77, s23, s7
	s_add_u32 s98, s16, s44
	s_addc_u32 s99, s17, s45
	global_load_lds_dwordx4 v163, s[98:99]
	s_add_i32 s92, s92, s5
	s_add_i32 m0, s92, 0x8000
	v_mov_b32_e32 v148, v163
	s_add_u32 s100, s76, s46
	s_addc_u32 s101, s77, s47
	global_load_lds_dwordx4 v162, s[100:101]
	s_add_i32 m0, s92, 0x8400
	s_add_u32 s98, s76, s48
	s_addc_u32 s99, s77, s49
	global_load_lds_dwordx4 v163, s[98:99]
	s_waitcnt lgkmcnt(0)
	s_barrier
	s_waitcnt lgkmcnt(0)
	v_mfma_f32_16x16x32_bf16 v[56:59], v[80:83], v[64:67], v[56:59]
	s_add_i32 s76, s4, s91
	v_mfma_f32_16x16x32_bf16 v[52:55], v[84:87], v[64:67], v[52:55]
	v_mfma_f32_16x16x32_bf16 v[48:51], v[88:91], v[64:67], v[48:51]
	v_mfma_f32_16x16x32_bf16 v[44:47], v[92:95], v[64:67], v[44:47]
	v_mfma_f32_16x16x32_bf16 v[40:43], v[80:83], v[68:71], v[40:43]
	v_mfma_f32_16x16x32_bf16 v[36:39], v[84:87], v[68:71], v[36:39]
	v_mfma_f32_16x16x32_bf16 v[32:35], v[88:91], v[68:71], v[32:35]
	v_mfma_f32_16x16x32_bf16 v[0:3], v[92:95], v[68:71], v[0:3]
	v_mov_b32_e32 v148, v162
	s_mov_b32 m0, s76
	s_add_u32 s100, s16, s38
	s_addc_u32 s101, s17, s39
	global_load_lds_dwordx4 v162, s[100:101]
	v_mfma_f32_16x16x32_bf16 v[28:31], v[80:83], v[72:75], v[28:31]
	v_mfma_f32_16x16x32_bf16 v[24:27], v[84:87], v[72:75], v[24:27]
	v_mfma_f32_16x16x32_bf16 v[20:23], v[88:91], v[72:75], v[20:23]
	v_mfma_f32_16x16x32_bf16 v[16:19], v[92:95], v[72:75], v[16:19]
	v_mfma_f32_16x16x32_bf16 v[12:15], v[80:83], v[76:79], v[12:15]
	v_mfma_f32_16x16x32_bf16 v[8:11], v[84:87], v[76:79], v[8:11]
	v_mfma_f32_16x16x32_bf16 v[4:7], v[88:91], v[76:79], v[4:7]
	v_mfma_f32_16x16x32_bf16 v[60:63], v[92:95], v[76:79], v[60:63]
	v_mov_b32_e32 v148, v163
	s_add_i32 m0, s76, 0x400
	s_add_u32 s98, s16, s40
	s_addc_u32 s99, s17, s41
	global_load_lds_dwordx4 v163, s[98:99]
	v_mfma_f32_16x16x32_bf16 v[56:59], v[112:115], v[96:99], v[56:59]
	v_mfma_f32_16x16x32_bf16 v[52:55], v[116:119], v[96:99], v[52:55]
	v_mfma_f32_16x16x32_bf16 v[48:51], v[120:123], v[96:99], v[48:51]
	v_mfma_f32_16x16x32_bf16 v[44:47], v[124:127], v[96:99], v[44:47]
	v_mfma_f32_16x16x32_bf16 v[40:43], v[112:115], v[100:103], v[40:43]
	v_mfma_f32_16x16x32_bf16 v[36:39], v[116:119], v[100:103], v[36:39]
	v_mfma_f32_16x16x32_bf16 v[32:35], v[120:123], v[100:103], v[32:35]
	v_mfma_f32_16x16x32_bf16 v[0:3], v[124:127], v[100:103], v[0:3]
	v_mov_b32_e32 v148, v162
	s_add_i32 m0, s76, 0x800
	s_add_u32 s100, s16, s42
	s_addc_u32 s101, s17, s43
	global_load_lds_dwordx4 v162, s[100:101]
	s_add_i32 s16, s73, 1
	v_mfma_f32_16x16x32_bf16 v[28:31], v[112:115], v[104:107], v[28:31]
	s_cmp_lg_u32 s73, 2
	s_cselect_b32 s73, s16, 0
	s_add_u32 s6, s6, 0x80
	v_mfma_f32_16x16x32_bf16 v[24:27], v[116:119], v[104:107], v[24:27]
	s_addc_u32 s7, s7, 0
	s_cmpk_eq_i32 s6, 0x680
	v_mfma_f32_16x16x32_bf16 v[20:23], v[120:123], v[104:107], v[20:23]
	v_mfma_f32_16x16x32_bf16 v[16:19], v[124:127], v[104:107], v[16:19]
	v_mfma_f32_16x16x32_bf16 v[12:15], v[112:115], v[108:111], v[12:15]
	v_mfma_f32_16x16x32_bf16 v[8:11], v[116:119], v[108:111], v[8:11]
	v_mfma_f32_16x16x32_bf16 v[4:7], v[120:123], v[108:111], v[4:7]
	v_mfma_f32_16x16x32_bf16 v[60:63], v[124:127], v[108:111], v[60:63]
	s_cbranch_scc0 .LBB0_1210
	s_waitcnt vmcnt(6) lgkmcnt(0)
	s_barrier
	s_mul_i32 s6, s73, 0xc000
	s_add_i32 s6, s6, 0
	v_add_u32_e32 v64, s6, v153
	v_add3_u32 v65, v64, s29, v169
	v_add3_u32 v64, v64, s28, v169
	v_add_u32_e32 v68, s6, v154
	ds_read_b128 v[124:127], v65
	ds_read_b128 v[120:123], v65 offset:2048
	ds_read_b128 v[96:99], v65 offset:4096
	ds_read_b128 v[92:95], v65 offset:6144
	ds_read_b128 v[108:111], v64 offset:32768
	ds_read_b128 v[112:115], v64 offset:34816
	ds_read_b128 v[116:119], v64 offset:36864
	ds_read_b128 v[100:103], v64 offset:38912
	v_add3_u32 v64, v68, s29, v169
	v_add3_u32 v68, v68, s28, v169
	ds_read_b128 v[88:91], v64
	ds_read_b128 v[104:107], v64 offset:2048
	ds_read_b128 v[72:75], v64 offset:4096
	ds_read_b128 v[64:67], v64 offset:6144
	ds_read_b128 v[76:79], v68 offset:32768
	ds_read_b128 v[80:83], v68 offset:34816
	ds_read_b128 v[84:87], v68 offset:36864
	ds_read_b128 v[68:71], v68 offset:38912
	s_waitcnt lgkmcnt(0)
	v_sub_co_u32_e64 v128, s[6:7], s73, 1
	s_and_b64 s[6:7], s[6:7], exec
	v_readfirstlane_b32 s6, v128
	s_cselect_b32 s91, 2, s6
	v_cndmask_b32_e64 v128, 0, 1, s[66:67]
	s_mov_b64 s[6:7], -1
	v_cmp_ne_u32_e64 s[8:9], 1, v128
	s_andn2_b64 vcc, exec, s[66:67]
	s_mul_i32 s23, s91, 0xc000
	s_cbranch_vccnz .LBB0_1213
	s_mul_i32 s22, s91, 0xc000
	s_mov_b64 s[6:7], 0

.LBB0_1356:
	s_waitcnt vmcnt(6) lgkmcnt(0)
	s_barrier
	s_waitcnt lgkmcnt(0)
	v_mfma_f32_16x16x32_bf16 v[124:127], v[52:55], v[64:67], v[124:127]
	s_mul_i32 vcc_lo, s93, 0xc000
	s_add_i32 s96, vcc_lo, 0xffff4000
	v_mfma_f32_16x16x32_bf16 v[120:123], v[48:51], v[64:67], v[120:123]
	s_cmp_lg_u32 s93, 0
	s_cselect_b32 vcc_hi, s96, 0x18000
	s_add_i32 s66, s3, vcc_hi
	v_mfma_f32_16x16x32_bf16 v[116:119], v[44:47], v[64:67], v[116:119]
	v_mfma_f32_16x16x32_bf16 v[64:67], v[40:43], v[64:67], v[112:115]
	v_mfma_f32_16x16x32_bf16 v[108:111], v[52:55], v[56:59], v[108:111]
	v_mfma_f32_16x16x32_bf16 v[104:107], v[48:51], v[56:59], v[104:107]
	v_mfma_f32_16x16x32_bf16 v[100:103], v[44:47], v[56:59], v[100:103]
	v_mfma_f32_16x16x32_bf16 v[56:59], v[40:43], v[56:59], v[96:99]
	s_add_u32 s96, s10, s8
	v_mov_b32_e32 v148, v178
	s_addc_u32 s97, s11, s9
	s_mov_b32 m0, s66
	s_add_u32 s98, s96, s44
	s_addc_u32 s99, s97, s45
	global_load_lds_dwordx4 v178, s[98:99]
	v_mfma_f32_16x16x32_bf16 v[92:95], v[52:55], v[36:39], v[92:95]
	v_mfma_f32_16x16x32_bf16 v[88:91], v[48:51], v[36:39], v[88:91]
	v_mfma_f32_16x16x32_bf16 v[84:87], v[44:47], v[36:39], v[84:87]
	v_mfma_f32_16x16x32_bf16 v[36:39], v[40:43], v[36:39], v[80:83]
	v_mfma_f32_16x16x32_bf16 v[52:55], v[52:55], v[32:35], v[76:79]
	v_mfma_f32_16x16x32_bf16 v[48:51], v[48:51], v[32:35], v[72:75]
	v_mfma_f32_16x16x32_bf16 v[44:47], v[44:47], v[32:35], v[68:71]
	v_mfma_f32_16x16x32_bf16 v[32:35], v[40:43], v[32:35], v[60:63]
	v_mov_b32_e32 v148, v179
	s_add_i32 m0, s66, 0x400
	s_add_u32 s100, s96, s46
	s_addc_u32 s101, s97, s47
	global_load_lds_dwordx4 v179, s[100:101]
	v_mfma_f32_16x16x32_bf16 v[124:127], v[20:23], v[28:31], v[124:127]
	v_mfma_f32_16x16x32_bf16 v[120:123], v[16:19], v[28:31], v[120:123]
	v_mfma_f32_16x16x32_bf16 v[116:119], v[12:15], v[28:31], v[116:119]
	v_mfma_f32_16x16x32_bf16 v[112:115], v[8:11], v[28:31], v[64:67]
	v_mfma_f32_16x16x32_bf16 v[108:111], v[20:23], v[24:27], v[108:111]
	v_mfma_f32_16x16x32_bf16 v[104:107], v[16:19], v[24:27], v[104:107]
	v_mfma_f32_16x16x32_bf16 v[100:103], v[12:15], v[24:27], v[100:103]
	v_mfma_f32_16x16x32_bf16 v[96:99], v[8:11], v[24:27], v[56:59]
	v_mov_b32_e32 v148, v178
	s_add_i32 m0, s66, 0x800
	s_add_u32 s98, s96, s48
	s_addc_u32 s99, s97, s49
	global_load_lds_dwordx4 v178, s[98:99]
	v_mfma_f32_16x16x32_bf16 v[92:95], v[20:23], v[4:7], v[92:95]
	s_waitcnt lgkmcnt(0)
	v_mfma_f32_16x16x32_bf16 v[88:91], v[16:19], v[4:7], v[88:91]
	v_mfma_f32_16x16x32_bf16 v[84:87], v[12:15], v[4:7], v[84:87]
	v_mfma_f32_16x16x32_bf16 v[80:83], v[8:11], v[4:7], v[36:39]
	v_mfma_f32_16x16x32_bf16 v[76:79], v[20:23], v[0:3], v[52:55]
	v_mfma_f32_16x16x32_bf16 v[72:75], v[16:19], v[0:3], v[48:51]
	v_mfma_f32_16x16x32_bf16 v[68:71], v[12:15], v[0:3], v[44:47]
	v_mfma_f32_16x16x32_bf16 v[60:63], v[8:11], v[0:3], v[32:35]
	s_barrier
	s_add_i32 s66, vcc_lo, 0
	v_add_u32_e32 v0, s66, v151
	v_add3_u32 v1, v0, s16, v169
	v_add3_u32 v0, v0, s5, v169
	v_add_u32_e32 v8, s66, v152
	ds_read_b128 v[64:67], v1
	ds_read_b128 v[56:59], v1 offset:2048
	ds_read_b128 v[36:39], v1 offset:4096
	ds_read_b128 v[32:35], v1 offset:6144
	ds_read_b128 v[52:55], v0 offset:32768
	ds_read_b128 v[48:51], v0 offset:34816
	ds_read_b128 v[44:47], v0 offset:36864
	ds_read_b128 v[40:43], v0 offset:38912
	v_add3_u32 v0, v8, s16, v169
	v_add3_u32 v8, v8, s5, v169
	ds_read_b128 v[28:31], v0
	ds_read_b128 v[24:27], v0 offset:2048
	ds_read_b128 v[4:7], v0 offset:4096
	ds_read_b128 v[0:3], v0 offset:6144
	ds_read_b128 v[20:23], v8 offset:32768
	ds_read_b128 v[16:19], v8 offset:34816
	ds_read_b128 v[12:15], v8 offset:36864
	ds_read_b128 v[8:11], v8 offset:38912
	s_waitcnt lgkmcnt(0)
	s_add_i32 s66, vcc_hi, 0
	s_add_i32 s67, s66, s2
	v_mov_b32_e32 v148, v179
	s_add_i32 m0, s67, 0xc00
	s_nop 0
	s_add_u32 s100, s96, s50
	s_addc_u32 s101, s97, s51
	s_add_u32 s96, s94, s8
	v_mov_b32_e32 v148, v178
	s_addc_u32 s97, s95, s9
	global_load_lds_dwordx4 v179, s[100:101]
	s_add_i32 s66, s66, s4
	s_add_i32 m0, s66, 0x8000
	v_mov_b32_e32 v148, v179
	s_add_u32 s98, s96, s52
	s_addc_u32 s99, s97, s53
	global_load_lds_dwordx4 v178, s[98:99]
	s_add_i32 m0, s66, 0x8400
	s_add_u32 s100, s96, s60
	s_addc_u32 s101, s97, s61
	global_load_lds_dwordx4 v179, s[100:101]
	s_add_i32 s66, s93, 1
	s_cmp_lg_u32 s93, 2
	s_cselect_b32 s93, s66, 0
	s_add_u32 s8, s8, 0x80
	s_addc_u32 s9, s9, 0
	s_cmpk_eq_i32 s8, 0x680
	s_cbranch_scc0 .LBB0_1356
	s_waitcnt vmcnt(6) lgkmcnt(0)
	s_barrier
	s_waitcnt lgkmcnt(0)
	v_mfma_f32_16x16x32_bf16 v[124:127], v[52:55], v[64:67], v[124:127]
	s_mul_i32 s11, s93, 0xc000
	s_add_i32 s8, s11, 0xffff4000
	v_mfma_f32_16x16x32_bf16 v[120:123], v[48:51], v[64:67], v[120:123]
	s_cmp_lg_u32 s93, 0
	s_cselect_b32 s10, s8, 0x18000
	s_andn2_b64 vcc, exec, s[70:71]
	v_mfma_f32_16x16x32_bf16 v[116:119], v[44:47], v[64:67], v[116:119]
	v_mfma_f32_16x16x32_bf16 v[64:67], v[40:43], v[64:67], v[112:115]
	v_mfma_f32_16x16x32_bf16 v[108:111], v[52:55], v[56:59], v[108:111]
	s_nop 1
	v_cndmask_b32_e64 v112, 0, 1, s[70:71]
	v_cmp_ne_u32_e64 s[8:9], 1, v112
	v_mfma_f32_16x16x32_bf16 v[104:107], v[48:51], v[56:59], v[104:107]
	v_mfma_f32_16x16x32_bf16 v[100:103], v[44:47], v[56:59], v[100:103]
	v_mfma_f32_16x16x32_bf16 v[140:143], v[40:43], v[56:59], v[96:99]
	s_cbranch_vccnz .LBB0_1359
	s_add_u32 s94, s86, s12
	v_mov_b32_e32 v56, v178
	s_addc_u32 s95, s87, s13
	s_add_i32 m0, s3, s10
	s_nop 0
	global_load_lds_dwordx4 v56, s[94:95]

.LBB0_1383:
	s_waitcnt vmcnt(6) lgkmcnt(0)
	s_barrier
	s_mul_i32 s73, s10, 0xc000
	s_add_i32 s74, s73, 0
	v_add_u32_e32 v80, s74, v151
	v_add_u32_e32 v112, s74, v152
	v_add3_u32 v76, v80, s16, v169
	v_add3_u32 v92, v80, s5, v169
	v_add3_u32 v108, v112, s16, v169
	v_add3_u32 v124, v112, s5, v169
	ds_read_b128 v[64:67], v76
	ds_read_b128 v[68:71], v76 offset:2048
	ds_read_b128 v[72:75], v76 offset:4096
	ds_read_b128 v[76:79], v76 offset:6144
	ds_read_b128 v[80:83], v92 offset:32768
	ds_read_b128 v[84:87], v92 offset:34816
	ds_read_b128 v[88:91], v92 offset:36864
	ds_read_b128 v[92:95], v92 offset:38912
	ds_read_b128 v[96:99], v108
	ds_read_b128 v[100:103], v108 offset:2048
	ds_read_b128 v[104:107], v108 offset:4096
	ds_read_b128 v[108:111], v108 offset:6144
	ds_read_b128 v[112:115], v124 offset:32768
	ds_read_b128 v[116:119], v124 offset:34816
	ds_read_b128 v[120:123], v124 offset:36864
	ds_read_b128 v[124:127], v124 offset:38912
	s_waitcnt lgkmcnt(0)
	s_add_i32 s73, s73, 0xffff4000
	s_cmp_lg_u32 s10, 0
	s_cselect_b32 s73, s73, 0x18000
	s_add_i32 s90, s73, 0
	s_add_u32 s74, s8, s6
	s_addc_u32 s75, s9, s7
	s_add_i32 s88, s90, s2
	v_mov_b32_e32 v148, v179
	s_add_i32 m0, s88, 0xc00
	s_add_u32 s88, s11, s6
	v_mov_b32_e32 v148, v178
	s_addc_u32 s89, s72, s7
	s_add_u32 s98, s74, s50
	s_addc_u32 s99, s75, s51
	global_load_lds_dwordx4 v179, s[98:99]
	s_add_i32 s90, s90, s4
	s_add_i32 m0, s90, 0x8000
	v_mov_b32_e32 v148, v179
	s_add_u32 s100, s88, s52
	s_addc_u32 s101, s89, s53
	global_load_lds_dwordx4 v178, s[100:101]
	s_add_i32 m0, s90, 0x8400
	s_add_u32 s98, s88, s60
	s_addc_u32 s99, s89, s61
	global_load_lds_dwordx4 v179, s[98:99]
	s_waitcnt lgkmcnt(0)
	s_barrier
	s_waitcnt lgkmcnt(0)
	v_mfma_f32_16x16x32_bf16 v[60:63], v[80:83], v[64:67], v[60:63]
	s_add_i32 s73, s3, s73
	v_mfma_f32_16x16x32_bf16 v[56:59], v[84:87], v[64:67], v[56:59]
	v_mfma_f32_16x16x32_bf16 v[52:55], v[88:91], v[64:67], v[52:55]
	v_mfma_f32_16x16x32_bf16 v[48:51], v[92:95], v[64:67], v[48:51]
	v_mfma_f32_16x16x32_bf16 v[44:47], v[80:83], v[68:71], v[44:47]
	v_mfma_f32_16x16x32_bf16 v[40:43], v[84:87], v[68:71], v[40:43]
	v_mfma_f32_16x16x32_bf16 v[36:39], v[88:91], v[68:71], v[36:39]
	v_mfma_f32_16x16x32_bf16 v[24:27], v[92:95], v[68:71], v[24:27]
	v_mov_b32_e32 v148, v178
	s_mov_b32 m0, s73
	s_add_u32 s100, s74, s44
	s_addc_u32 s101, s75, s45
	global_load_lds_dwordx4 v178, s[100:101]
	v_mfma_f32_16x16x32_bf16 v[20:23], v[80:83], v[72:75], v[20:23]
	v_mfma_f32_16x16x32_bf16 v[16:19], v[84:87], v[72:75], v[16:19]
	v_mfma_f32_16x16x32_bf16 v[12:15], v[88:91], v[72:75], v[12:15]
	v_mfma_f32_16x16x32_bf16 v[8:11], v[92:95], v[72:75], v[8:11]
	v_mfma_f32_16x16x32_bf16 v[4:7], v[80:83], v[76:79], v[4:7]
	v_mfma_f32_16x16x32_bf16 v[0:3], v[84:87], v[76:79], v[0:3]
	v_mfma_f32_16x16x32_bf16 v[28:31], v[88:91], v[76:79], v[28:31]
	v_mfma_f32_16x16x32_bf16 v[32:35], v[92:95], v[76:79], v[32:35]
	v_mov_b32_e32 v148, v179
	s_add_i32 m0, s73, 0x400
	s_add_u32 s98, s74, s46
	s_addc_u32 s99, s75, s47
	global_load_lds_dwordx4 v179, s[98:99]
	v_mfma_f32_16x16x32_bf16 v[60:63], v[112:115], v[96:99], v[60:63]
	v_mfma_f32_16x16x32_bf16 v[56:59], v[116:119], v[96:99], v[56:59]
	v_mfma_f32_16x16x32_bf16 v[52:55], v[120:123], v[96:99], v[52:55]
	v_mfma_f32_16x16x32_bf16 v[48:51], v[124:127], v[96:99], v[48:51]
	v_mfma_f32_16x16x32_bf16 v[44:47], v[112:115], v[100:103], v[44:47]
	v_mfma_f32_16x16x32_bf16 v[40:43], v[116:119], v[100:103], v[40:43]
	v_mfma_f32_16x16x32_bf16 v[36:39], v[120:123], v[100:103], v[36:39]
	v_mfma_f32_16x16x32_bf16 v[24:27], v[124:127], v[100:103], v[24:27]
	v_mov_b32_e32 v148, v178
	s_add_i32 m0, s73, 0x800
	s_add_u32 s100, s74, s48
	s_addc_u32 s101, s75, s49
	global_load_lds_dwordx4 v178, s[100:101]
	s_add_i32 s73, s10, 1
	v_mfma_f32_16x16x32_bf16 v[20:23], v[112:115], v[104:107], v[20:23]
	s_cmp_lg_u32 s10, 2
	s_cselect_b32 s10, s73, 0
	s_add_u32 s6, s6, 0x80
	v_mfma_f32_16x16x32_bf16 v[16:19], v[116:119], v[104:107], v[16:19]
	s_addc_u32 s7, s7, 0
	s_cmpk_eq_i32 s6, 0x680
	v_mfma_f32_16x16x32_bf16 v[12:15], v[120:123], v[104:107], v[12:15]
	v_mfma_f32_16x16x32_bf16 v[8:11], v[124:127], v[104:107], v[8:11]
	v_mfma_f32_16x16x32_bf16 v[4:7], v[112:115], v[108:111], v[4:7]
	v_mfma_f32_16x16x32_bf16 v[0:3], v[116:119], v[108:111], v[0:3]
	v_mfma_f32_16x16x32_bf16 v[28:31], v[120:123], v[108:111], v[28:31]
	v_mfma_f32_16x16x32_bf16 v[32:35], v[124:127], v[108:111], v[32:35]
	s_cbranch_scc0 .LBB0_1383
	s_waitcnt vmcnt(6) lgkmcnt(0)
	s_barrier
	s_mul_i32 s6, s10, 0xc000
	s_add_i32 s6, s6, 0
	v_add_u32_e32 v64, s6, v151
	v_add3_u32 v65, v64, s16, v169
	v_add3_u32 v64, v64, s5, v169
	v_add_u32_e32 v68, s6, v152
	ds_read_b128 v[124:127], v65
	ds_read_b128 v[120:123], v65 offset:2048
	ds_read_b128 v[100:103], v65 offset:4096
	ds_read_b128 v[96:99], v65 offset:6144
	ds_read_b128 v[108:111], v64 offset:32768
	ds_read_b128 v[112:115], v64 offset:34816
	ds_read_b128 v[116:119], v64 offset:36864
	ds_read_b128 v[104:107], v64 offset:38912
	v_add3_u32 v64, v68, s16, v169
	v_add3_u32 v68, v68, s5, v169
	ds_read_b128 v[92:95], v64
	ds_read_b128 v[88:91], v64 offset:2048
	ds_read_b128 v[72:75], v64 offset:4096
	ds_read_b128 v[64:67], v64 offset:6144
	ds_read_b128 v[76:79], v68 offset:32768
	ds_read_b128 v[80:83], v68 offset:34816
	ds_read_b128 v[84:87], v68 offset:36864
	ds_read_b128 v[68:71], v68 offset:38912
	s_waitcnt lgkmcnt(0)
	v_sub_co_u32_e64 v128, s[6:7], s10, 1
	s_and_b64 s[6:7], s[6:7], exec
	v_readfirstlane_b32 s6, v128
	s_cselect_b32 s73, 2, s6
	v_cndmask_b32_e64 v128, 0, 1, s[68:69]
	s_mov_b64 s[6:7], -1
	v_cmp_ne_u32_e64 s[8:9], 1, v128
	s_andn2_b64 vcc, exec, s[68:69]
	s_mul_i32 s72, s73, 0xc000
	s_cbranch_vccnz .LBB0_1386
	s_mul_i32 s11, s73, 0xc000
	s_mov_b64 s[6:7], 0

.LBB0_1472:
	s_waitcnt vmcnt(6) lgkmcnt(0)
	s_barrier
	s_waitcnt lgkmcnt(0)
	v_mfma_f32_16x16x32_bf16 v[124:127], v[52:55], v[64:67], v[124:127]
	s_mul_i32 s93, s90, 0xc000
	s_add_i32 s94, s93, 0xffff4000
	v_mfma_f32_16x16x32_bf16 v[120:123], v[48:51], v[64:67], v[120:123]
	s_cmp_lg_u32 s90, 0
	s_cselect_b32 vcc_lo, s94, 0x18000
	s_add_i32 vcc_hi, s17, vcc_lo
	v_mfma_f32_16x16x32_bf16 v[116:119], v[44:47], v[64:67], v[116:119]
	v_mfma_f32_16x16x32_bf16 v[64:67], v[40:43], v[64:67], v[112:115]
	v_mfma_f32_16x16x32_bf16 v[108:111], v[52:55], v[56:59], v[108:111]
	v_mfma_f32_16x16x32_bf16 v[104:107], v[48:51], v[56:59], v[104:107]
	v_mfma_f32_16x16x32_bf16 v[100:103], v[44:47], v[56:59], v[100:103]
	v_mfma_f32_16x16x32_bf16 v[56:59], v[40:43], v[56:59], v[96:99]
	s_add_u32 s94, s10, s6
	v_mov_b32_e32 v146, v164
	s_addc_u32 s95, s11, s7
	s_mov_b64 s[96:97], 0x4400180
	s_mov_b32 m0, vcc_hi
	s_nop 0
	s_add_u32 s98, s94, 0x4400180
	s_addc_u32 s99, s95, 0x0
	global_load_lds_dwordx4 v164, s[98:99]
	v_mfma_f32_16x16x32_bf16 v[92:95], v[52:55], v[36:39], v[92:95]
	v_mfma_f32_16x16x32_bf16 v[88:91], v[48:51], v[36:39], v[88:91]
	v_mfma_f32_16x16x32_bf16 v[84:87], v[44:47], v[36:39], v[84:87]
	v_mfma_f32_16x16x32_bf16 v[36:39], v[40:43], v[36:39], v[80:83]
	v_mfma_f32_16x16x32_bf16 v[52:55], v[52:55], v[32:35], v[76:79]
	v_mfma_f32_16x16x32_bf16 v[48:51], v[48:51], v[32:35], v[72:75]
	v_mfma_f32_16x16x32_bf16 v[44:47], v[44:47], v[32:35], v[68:71]
	v_mfma_f32_16x16x32_bf16 v[32:35], v[40:43], v[32:35], v[60:63]
	v_mov_b32_e32 v146, v165
	s_mov_b64 s[96:97], 0x440b180
	s_add_i32 m0, vcc_hi, 0x400
	s_nop 0
	s_add_u32 s100, s94, 0x440b180
	s_addc_u32 s101, s95, 0x0
	global_load_lds_dwordx4 v165, s[100:101]
	v_mfma_f32_16x16x32_bf16 v[124:127], v[20:23], v[28:31], v[124:127]
	v_mfma_f32_16x16x32_bf16 v[120:123], v[16:19], v[28:31], v[120:123]
	v_mfma_f32_16x16x32_bf16 v[116:119], v[12:15], v[28:31], v[116:119]
	v_mfma_f32_16x16x32_bf16 v[112:115], v[8:11], v[28:31], v[64:67]
	v_mfma_f32_16x16x32_bf16 v[108:111], v[20:23], v[24:27], v[108:111]
	v_mfma_f32_16x16x32_bf16 v[104:107], v[16:19], v[24:27], v[104:107]
	v_mfma_f32_16x16x32_bf16 v[100:103], v[12:15], v[24:27], v[100:103]
	v_mfma_f32_16x16x32_bf16 v[96:99], v[8:11], v[24:27], v[56:59]
	v_mov_b32_e32 v146, v164
	s_mov_b64 s[96:97], 0x4416180
	s_add_i32 m0, vcc_hi, 0x800
	s_nop 0
	s_add_u32 s98, s94, 0x4416180
	s_addc_u32 s99, s95, 0x0
	global_load_lds_dwordx4 v164, s[98:99]
	v_mfma_f32_16x16x32_bf16 v[92:95], v[20:23], v[4:7], v[92:95]
	s_waitcnt lgkmcnt(0)
	v_mfma_f32_16x16x32_bf16 v[88:91], v[16:19], v[4:7], v[88:91]
	v_mfma_f32_16x16x32_bf16 v[84:87], v[12:15], v[4:7], v[84:87]
	v_mfma_f32_16x16x32_bf16 v[80:83], v[8:11], v[4:7], v[36:39]
	v_mfma_f32_16x16x32_bf16 v[76:79], v[20:23], v[0:3], v[52:55]
	v_mfma_f32_16x16x32_bf16 v[72:75], v[16:19], v[0:3], v[48:51]
	v_mfma_f32_16x16x32_bf16 v[68:71], v[12:15], v[0:3], v[44:47]
	v_mfma_f32_16x16x32_bf16 v[60:63], v[8:11], v[0:3], v[32:35]
	s_barrier
	s_add_i32 s93, s93, 0
	v_add_u32_e32 v0, s93, v151
	v_add3_u32 v1, v0, s33, v169
	v_add3_u32 v0, v0, s29, v169
	v_add_u32_e32 v8, s93, v152
	ds_read_b128 v[64:67], v1
	ds_read_b128 v[56:59], v1 offset:2048
	ds_read_b128 v[36:39], v1 offset:4096
	ds_read_b128 v[32:35], v1 offset:6144
	ds_read_b128 v[52:55], v0 offset:32768
	ds_read_b128 v[48:51], v0 offset:34816
	ds_read_b128 v[44:47], v0 offset:36864
	ds_read_b128 v[40:43], v0 offset:38912
	v_add3_u32 v0, v8, s33, v169
	v_add3_u32 v8, v8, s29, v169
	ds_read_b128 v[28:31], v0
	ds_read_b128 v[24:27], v0 offset:2048
	ds_read_b128 v[4:7], v0 offset:4096
	ds_read_b128 v[0:3], v0 offset:6144
	ds_read_b128 v[20:23], v8 offset:32768
	ds_read_b128 v[16:19], v8 offset:34816
	ds_read_b128 v[12:15], v8 offset:36864
	ds_read_b128 v[8:11], v8 offset:38912
	s_waitcnt lgkmcnt(0)
	v_mov_b32_e32 v146, v165
	s_add_i32 s93, vcc_lo, 0
	s_mov_b64 s[96:97], 0x2980180
	s_add_u32 s100, s94, 0x4421180
	s_addc_u32 s101, s95, 0x0
	s_mov_b64 s[94:95], 0x4421180
	s_add_i32 s94, s93, s16
	s_add_i32 m0, s94, 0xc00
	s_add_u32 s94, s91, s6
	v_mov_b32_e32 v146, v164
	s_addc_u32 s95, s92, s7
	global_load_lds_dwordx4 v165, s[100:101]
	s_add_i32 s93, s93, s28
	s_add_i32 m0, s93, 0x8000
	v_mov_b32_e32 v146, v165
	s_add_u32 s98, s94, 0x2980180
	s_addc_u32 s99, s95, 0x0
	global_load_lds_dwordx4 v164, s[98:99]
	s_add_i32 m0, s93, 0x8400
	s_add_u32 s100, s94, 0x298b180
	s_addc_u32 s101, s95, 0x0
	s_mov_b64 s[94:95], 0x298b180
	global_load_lds_dwordx4 v165, s[100:101]
	s_add_i32 s93, s90, 1
	s_cmp_lg_u32 s90, 2
	s_cselect_b32 s90, s93, 0
	s_add_u32 s6, s6, 0x80
	s_addc_u32 s7, s7, 0
	s_cmpk_eq_i32 s6, 0x1480
	s_cbranch_scc0 .LBB0_1472
	s_waitcnt vmcnt(6) lgkmcnt(0)
	s_barrier
	s_waitcnt lgkmcnt(0)
	v_mfma_f32_16x16x32_bf16 v[124:127], v[52:55], v[64:67], v[124:127]
	s_mul_i32 s11, s90, 0xc000
	s_add_i32 s6, s11, 0xffff4000
	v_mfma_f32_16x16x32_bf16 v[120:123], v[48:51], v[64:67], v[120:123]
	s_cmp_lg_u32 s90, 0
	s_cselect_b32 s10, s6, 0x18000
	s_andn2_b64 vcc, exec, s[52:53]
	v_mfma_f32_16x16x32_bf16 v[116:119], v[44:47], v[64:67], v[116:119]
	v_mfma_f32_16x16x32_bf16 v[64:67], v[40:43], v[64:67], v[112:115]
	v_mfma_f32_16x16x32_bf16 v[108:111], v[52:55], v[56:59], v[108:111]
	s_nop 1
	v_cndmask_b32_e64 v112, 0, 1, s[52:53]
	v_cmp_ne_u32_e64 s[6:7], 1, v112
	v_mfma_f32_16x16x32_bf16 v[104:107], v[48:51], v[56:59], v[104:107]
	v_mfma_f32_16x16x32_bf16 v[100:103], v[44:47], v[56:59], v[100:103]
	v_mfma_f32_16x16x32_bf16 v[140:143], v[40:43], v[56:59], v[96:99]
	s_cbranch_vccnz .LBB0_1475
	s_add_u32 s92, s51, s8
	v_mov_b32_e32 v56, v164
	s_addc_u32 s93, s82, s9
	s_add_i32 m0, s17, s10
	s_nop 0
	global_load_lds_dwordx4 v56, s[92:93]

	.amdhsa_kernel _Z4mega6Params
		.amdhsa_group_segment_fixed_size 0
		.amdhsa_private_segment_fixed_size 0
		.amdhsa_kernarg_size 440
		.amdhsa_user_sgpr_count 2
		.amdhsa_user_sgpr_dispatch_ptr 0
		.amdhsa_user_sgpr_queue_ptr 0
		.amdhsa_user_sgpr_kernarg_segment_ptr 1
		.amdhsa_user_sgpr_dispatch_id 0
		.amdhsa_user_sgpr_kernarg_preload_length 0
		.amdhsa_user_sgpr_kernarg_preload_offset 0
		.amdhsa_user_sgpr_private_segment_size 0
		.amdhsa_uses_dynamic_stack 0
		.amdhsa_enable_private_segment 0
		.amdhsa_system_sgpr_workgroup_id_x 1
		.amdhsa_system_sgpr_workgroup_id_y 0
		.amdhsa_system_sgpr_workgroup_id_z 0
		.amdhsa_system_sgpr_workgroup_info 0
		.amdhsa_system_vgpr_workitem_id 2
		.amdhsa_next_free_vgpr 220
		.amdhsa_next_free_sgpr 102
		.amdhsa_accum_offset 220
		.amdhsa_reserve_vcc 1
		.amdhsa_float_round_mode_32 0
		.amdhsa_float_round_mode_16_64 0
		.amdhsa_float_denorm_mode_32 3
		.amdhsa_float_denorm_mode_16_64 3
		.amdhsa_dx10_clamp 1
		.amdhsa_ieee_mode 1
		.amdhsa_fp16_overflow 0
		.amdhsa_tg_split 0
		.amdhsa_exception_fp_ieee_invalid_op 0
		.amdhsa_exception_fp_denorm_src 0
		.amdhsa_exception_fp_ieee_div_zero 0
		.amdhsa_exception_fp_ieee_overflow 0
		.amdhsa_exception_fp_ieee_underflow 0
		.amdhsa_exception_fp_ieee_inexact 0
		.amdhsa_exception_int_div_zero 0
	.end_amdhsa_kernel

amdhsa.kernels:
  - .agpr_count:     0
    .args:
      - .offset:         0
        .size:           184
        .value_kind:     by_value
      - .offset:         184
        .size:           4
        .value_kind:     hidden_block_count_x
      - .offset:         188
        .size:           4
        .value_kind:     hidden_block_count_y
      - .offset:         192
        .size:           4
        .value_kind:     hidden_block_count_z
      - .offset:         196
        .size:           2
        .value_kind:     hidden_group_size_x
      - .offset:         198
        .size:           2
        .value_kind:     hidden_group_size_y
      - .offset:         200
        .size:           2
        .value_kind:     hidden_group_size_z
      - .offset:         202
        .size:           2
        .value_kind:     hidden_remainder_x
      - .offset:         204
        .size:           2
        .value_kind:     hidden_remainder_y
      - .offset:         206
        .size:           2
        .value_kind:     hidden_remainder_z
      - .offset:         224
        .size:           8
        .value_kind:     hidden_global_offset_x
      - .offset:         232
        .size:           8
        .value_kind:     hidden_global_offset_y
      - .offset:         240
        .size:           8
        .value_kind:     hidden_global_offset_z
      - .offset:         248
        .size:           2
        .value_kind:     hidden_grid_dims
      - .offset:         272
        .size:           8
        .value_kind:     hidden_multigrid_sync_arg
      - .offset:         304
        .size:           4
        .value_kind:     hidden_dynamic_lds_size
    .group_segment_fixed_size: 0
    .kernarg_segment_align: 8
    .kernarg_segment_size: 440
    .language:       OpenCL C
    .language_version:
      - 2
      - 0
    .max_flat_workgroup_size: 512
    .name:           _Z4mega6Params
    .private_segment_fixed_size: 0
    .sgpr_count:     108
    .sgpr_spill_count: 82
    .symbol:         _Z4mega6Params.kd
    .uniform_work_group_size: 1
    .uses_dynamic_stack: false
    .vgpr_count:     220
    .vgpr_spill_count: 0
    .wavefront_size: 64
